# out-proj / down-proj exposed epilogue: second residual batch's lines requested (dead registers) right after the first batch is issued
# speedup vs baseline: 1.0058x; 1.0027x over previous
; #define PG8_STAGE(bufoff, gbase, voff) do { _Pragma("unroll") for (int _i = 0; _i < 2; ++_i) \
;         __builtin_amdgcn_global_load_lds((const unsigned*)((const char*)(gbase) + (voff)[_i]), (PG8_LAS unsigned*)(lds + (bufoff) + ldsw + _i * 8192), 16, 0, 0); } while (0)
; #define PG8_LDA(dst, b, h) do { _Pragma("unroll") for (int m = 0; m < 4; ++m) _Pragma("unroll") for (int k = 0; k < 2; ++k) dst[m][k] = *(const PG8_LAS bf16x8*)(lds + PG8_SA(b, h) + aoff + m * 2048 + k * 1024); } while (0)
; #define PG8_LDB(dst, b, h) do { _Pragma("unroll") for (int n = 0; n < 2; ++n) _Pragma("unroll") for (int k = 0; k < 2; ++k) dst[n][k] = *(const PG8_LAS bf16x8*)(lds + PG8_SB(b, h) + boff + n * 2048 + k * 1024); } while (0)
; #define PG8_MMA(ai, bj, At, Bt) do { __builtin_amdgcn_s_setprio(1); _Pragma("unroll") for (int m = 0; m < 4; ++m) _Pragma("unroll") for (int n = 0; n < 2; ++n) _Pragma("unroll") for (int k = 0; k < 2; ++k) \
;         acc[ai][bj][m][n] = __builtin_amdgcn_mfma_f32_16x16x32_bf16(Bt[n][k], At[m][k], acc[ai][bj][m][n], 0, 0, 0); __builtin_amdgcn_s_setprio(0); } while (0)
; #define PG8_WAIT_V(n) asm volatile("s_waitcnt vmcnt(" #n ")" ::: "memory")
; #define PG8_BAR __builtin_amdgcn_s_barrier()
; template <class Epi, class Sched, bool ALIGN_EPI = false, bool SP2 = false>
; __device__ __forceinline__ void gemm_phase(PG8_LAS unsigned char* lds, const Gemm g, const Sched& S, const Epi& E) {
;     ...
;         for (int t = 0; t < nt; t += 2) {
;             const bool last = (t == nt - 2);
;             const char* a1 = cA + (size_t)(t + 1) * kstep;
;             const char* a2 = last ? nA : cA + (size_t)(t + 2) * kstep; const char* b2 = last ? nB : cB + (size_t)(t + 2) * kstep;
;             const char* a3 = a2 + kstep; const char* b3 = b2 + kstep;
;             if (last && has_next) S.a_ready(nxt);
;             if constexpr (SP2) {
;             PG8_LDB(B0, 0, 0); PG8_LDB(B1, 0, 1); PG8_SCHED; PG8_LDA(At, 0, 0); PG8_STAGE(PG8_SA(1, 1), a1 + hstep, voffA);
;             PG8_WAIT_V(8); PG8_WAIT_L(0); PG8_BAR; PG8_MMA(0, 0, At, B0); PG8_MMA(0, 1, At, B1); PG8_BAR; PG8_SCHED;
;             PG8_LDA(At, 0, 1); PG8_STAGE(PG8_SB(0, 0), b2, voffB); PG8_STAGE(PG8_SB(0, 1), b2 + hstep, voffB); PG8_STAGE(PG8_SA(0, 0), a2, voffA);
;             PG8_WAIT_V(8); PG8_WAIT_L(0); PG8_BAR; PG8_MMA(1, 0, At, B0); PG8_MMA(1, 1, At, B1); PG8_BAR; PG8_SCHED;
.LBB0_2046:
	s_add_u32 s20, s44, 0xfff80080
	s_addc_u32 s21, s45, -1
	s_add_i32 s30, 0, 0x10000
	s_cmp_eq_u32 s59, 28
	s_cselect_b32 s47, s12, s21
	s_cselect_b32 s46, s13, s20
	s_cselect_b32 s21, s23, s58
	s_cselect_b32 s20, s25, s33
	s_add_i32 s60, 0, 0x14000
	s_waitcnt vmcnt(0) lgkmcnt(0)
	v_add_u32_e32 v80, s30, v212
	v_add_u32_e32 v160, s60, v212
	ds_read_b128 v[60:63], v80
	ds_read_b128 v[64:67], v80 offset:1024
	ds_read_b128 v[76:79], v80 offset:2048
	ds_read_b128 v[80:83], v80 offset:3072
	ds_read_b128 v[148:151], v160
	ds_read_b128 v[152:155], v160 offset:1024
	ds_read_b128 v[156:159], v160 offset:2048
	ds_read_b128 v[160:163], v160 offset:3072
	v_lshl_add_u64 v[206:207], s[44:45], 0, v[188:189]
	s_add_i32 m0, s43, 0xc000
	ds_read_b128 v[164:167], v218
	ds_read_b128 v[168:171], v218 offset:1024
	ds_read_b128 v[172:175], v218 offset:2048
	ds_read_b128 v[176:179], v218 offset:3072
	ds_read_b128 v[190:193], v218 offset:4096
	ds_read_b128 v[194:197], v218 offset:5120
	ds_read_b128 v[198:201], v218 offset:6144
	ds_read_b128 v[202:205], v218 offset:7168
	global_load_lds_dwordx4 v[206:207], off
	v_lshl_add_u64 v[206:207], s[44:45], 0, v[186:187]
	s_add_i32 m0, s43, 0xe000
	s_nop 0
	global_load_lds_dwordx4 v[206:207], off
	s_waitcnt vmcnt(8)
	s_waitcnt lgkmcnt(0)
	s_barrier
	s_setprio 1
	s_waitcnt lgkmcnt(0)
	v_mfma_f32_16x16x32_bf16 v[144:147], v[60:63], v[164:167], v[144:147]
	v_mfma_f32_16x16x32_bf16 v[140:143], v[76:79], v[164:167], v[140:143]
	v_mfma_f32_16x16x32_bf16 v[136:139], v[60:63], v[172:175], v[136:139]
	v_mfma_f32_16x16x32_bf16 v[132:135], v[76:79], v[172:175], v[132:135]
	v_mfma_f32_16x16x32_bf16 v[112:115], v[60:63], v[190:193], v[112:115]
	v_mfma_f32_16x16x32_bf16 v[108:111], v[76:79], v[190:193], v[108:111]
	v_mfma_f32_16x16x32_bf16 v[104:107], v[60:63], v[198:201], v[104:107]
	v_mfma_f32_16x16x32_bf16 v[100:103], v[76:79], v[198:201], v[100:103]
	v_mfma_f32_16x16x32_bf16 v[144:147], v[64:67], v[168:171], v[144:147]
	v_mfma_f32_16x16x32_bf16 v[140:143], v[80:83], v[168:171], v[140:143]
	v_mfma_f32_16x16x32_bf16 v[136:139], v[64:67], v[176:179], v[136:139]
	v_mfma_f32_16x16x32_bf16 v[132:135], v[80:83], v[176:179], v[132:135]
	v_mfma_f32_16x16x32_bf16 v[112:115], v[64:67], v[194:197], v[112:115]
	v_mfma_f32_16x16x32_bf16 v[108:111], v[80:83], v[194:197], v[108:111]
	v_mfma_f32_16x16x32_bf16 v[104:107], v[64:67], v[202:205], v[104:107]
	v_mfma_f32_16x16x32_bf16 v[100:103], v[80:83], v[202:205], v[100:103]
	s_setprio 0
	s_setprio 1
	v_mfma_f32_16x16x32_bf16 v[128:131], v[148:151], v[164:167], v[128:131]
	v_mfma_f32_16x16x32_bf16 v[124:127], v[156:159], v[164:167], v[124:127]
	v_mfma_f32_16x16x32_bf16 v[120:123], v[148:151], v[172:175], v[120:123]
	v_mfma_f32_16x16x32_bf16 v[116:119], v[156:159], v[172:175], v[116:119]
	v_mfma_f32_16x16x32_bf16 v[96:99], v[148:151], v[190:193], v[96:99]
	v_mfma_f32_16x16x32_bf16 v[92:95], v[156:159], v[190:193], v[92:95]
	v_mfma_f32_16x16x32_bf16 v[88:91], v[148:151], v[198:201], v[88:91]
	v_mfma_f32_16x16x32_bf16 v[84:87], v[156:159], v[198:201], v[84:87]
	v_mfma_f32_16x16x32_bf16 v[128:131], v[152:155], v[168:171], v[128:131]
	v_mfma_f32_16x16x32_bf16 v[124:127], v[160:163], v[168:171], v[124:127]
	v_mfma_f32_16x16x32_bf16 v[120:123], v[152:155], v[176:179], v[120:123]
	v_mfma_f32_16x16x32_bf16 v[116:119], v[160:163], v[176:179], v[116:119]
	v_mfma_f32_16x16x32_bf16 v[96:99], v[152:155], v[194:197], v[96:99]
	v_mfma_f32_16x16x32_bf16 v[92:95], v[160:163], v[194:197], v[92:95]
	v_mfma_f32_16x16x32_bf16 v[88:91], v[152:155], v[202:205], v[88:91]
	v_mfma_f32_16x16x32_bf16 v[84:87], v[160:163], v[202:205], v[84:87]
	s_setprio 0
	s_barrier
	s_add_i32 s30, s30, s9
	v_lshl_add_u64 v[206:207], s[20:21], 0, v[2:3]
	s_mov_b32 m0, s30
	ds_read_b128 v[164:167], v218 offset:16384
	ds_read_b128 v[168:171], v218 offset:17408
	ds_read_b128 v[172:175], v218 offset:18432
	ds_read_b128 v[176:179], v218 offset:19456
	ds_read_b128 v[190:193], v218 offset:20480
	ds_read_b128 v[194:197], v218 offset:21504
	ds_read_b128 v[198:201], v218 offset:22528
	ds_read_b128 v[202:205], v218 offset:23552
	global_load_lds_dwordx4 v[206:207], off
	s_add_i32 m0, s30, 0x2000
	s_add_u32 s30, s20, 0x80000
	v_lshl_add_u64 v[208:209], s[20:21], 0, v[184:185]
	s_addc_u32 s31, s21, 0
	s_add_i32 s60, s60, s9
	global_load_lds_dwordx4 v[208:209], off
	v_lshl_add_u64 v[210:211], s[30:31], 0, v[2:3]
	s_mov_b32 m0, s60
	v_lshl_add_u64 v[214:215], s[46:47], 0, v[182:183]
	global_load_lds_dwordx4 v[210:211], off
	v_lshl_add_u64 v[210:211], s[30:31], 0, v[184:185]
	s_add_i32 m0, s60, 0x2000
	s_nop 0
	global_load_lds_dwordx4 v[210:211], off
	v_lshl_add_u64 v[210:211], s[46:47], 0, v[180:181]
	s_mov_b32 m0, s43
	s_nop 0
	global_load_lds_dwordx4 v[210:211], off
	s_mov_b32 m0, s50
	s_nop 0
	global_load_lds_dwordx4 v[214:215], off
	s_waitcnt vmcnt(8)
	s_waitcnt lgkmcnt(0)
	s_barrier
; #define PG8_STAGE(bufoff, gbase, voff) do { _Pragma("unroll") for (int _i = 0; _i < 2; ++_i) \
;         __builtin_amdgcn_global_load_lds((const unsigned*)((const char*)(gbase) + (voff)[_i]), (PG8_LAS unsigned*)(lds + (bufoff) + ldsw + _i * 8192), 16, 0, 0); } while (0)
; #define PG8_LDA(dst, b, h) do { _Pragma("unroll") for (int m = 0; m < 4; ++m) _Pragma("unroll") for (int k = 0; k < 2; ++k) dst[m][k] = *(const PG8_LAS bf16x8*)(lds + PG8_SA(b, h) + aoff + m * 2048 + k * 1024); } while (0)
; #define PG8_LDB(dst, b, h) do { _Pragma("unroll") for (int n = 0; n < 2; ++n) _Pragma("unroll") for (int k = 0; k < 2; ++k) dst[n][k] = *(const PG8_LAS bf16x8*)(lds + PG8_SB(b, h) + boff + n * 2048 + k * 1024); } while (0)
; #define PG8_MMA(ai, bj, At, Bt) do { __builtin_amdgcn_s_setprio(1); _Pragma("unroll") for (int m = 0; m < 4; ++m) _Pragma("unroll") for (int n = 0; n < 2; ++n) _Pragma("unroll") for (int k = 0; k < 2; ++k) \
;         acc[ai][bj][m][n] = __builtin_amdgcn_mfma_f32_16x16x32_bf16(Bt[n][k], At[m][k], acc[ai][bj][m][n], 0, 0, 0); __builtin_amdgcn_s_setprio(0); } while (0)
; #define PG8_WAIT_V(n) asm volatile("s_waitcnt vmcnt(" #n ")" ::: "memory")
; #define PG8_WAIT_L(n) asm volatile("s_waitcnt lgkmcnt(" #n ")" ::: "memory")
; #define PG8_BAR __builtin_amdgcn_s_barrier()
; #define PG8_SCHED __builtin_amdgcn_sched_barrier(0)
; template <class Epi, class Sched, bool ALIGN_EPI = false, bool SP2 = false>
; __device__ __forceinline__ void gemm_phase(PG8_LAS unsigned char* lds, const Gemm g, const Sched& S, const Epi& E) {
;     ...
;             PG8_LDA(At, 0, 1); PG8_STAGE(PG8_SB(0, 0), b2, voffB); PG8_STAGE(PG8_SB(0, 1), b2 + hstep, voffB); PG8_STAGE(PG8_SA(0, 0), a2, voffA);
;             PG8_WAIT_V(8); PG8_WAIT_L(0); PG8_BAR; PG8_MMA(1, 0, At, B0); PG8_MMA(1, 1, At, B1); PG8_BAR; PG8_SCHED;
;             PG8_LDB(B0, 1, 0); PG8_LDB(B1, 1, 1); PG8_SCHED; PG8_LDA(At, 1, 0); PG8_STAGE(PG8_SA(0, 1), a2 + hstep, voffA);
;             PG8_WAIT_V(8); PG8_WAIT_L(0); PG8_BAR; PG8_MMA(0, 0, At, B0); PG8_MMA(0, 1, At, B1); PG8_BAR; PG8_SCHED;
;             PG8_LDA(At, 1, 1); PG8_STAGE(PG8_SB(1, 0), b3, voffB); PG8_STAGE(PG8_SB(1, 1), b3 + hstep, voffB); PG8_STAGE(PG8_SA(1, 0), a3, voffA);
;             PG8_WAIT_V(8); PG8_WAIT_L(0); PG8_BAR; PG8_MMA(1, 0, At, B0); PG8_MMA(1, 1, At, B1); PG8_BAR; PG8_SCHED;
	s_setprio 1
	s_waitcnt lgkmcnt(0)
	v_mfma_f32_16x16x32_bf16 v[72:75], v[60:63], v[164:167], v[72:75]
	v_mfma_f32_16x16x32_bf16 v[68:71], v[76:79], v[164:167], v[68:71]
	v_mfma_f32_16x16x32_bf16 v[56:59], v[60:63], v[172:175], v[56:59]
	v_mfma_f32_16x16x32_bf16 v[52:55], v[76:79], v[172:175], v[52:55]
	v_mfma_f32_16x16x32_bf16 v[32:35], v[60:63], v[190:193], v[32:35]
	v_mfma_f32_16x16x32_bf16 v[28:31], v[76:79], v[190:193], v[28:31]
	v_mfma_f32_16x16x32_bf16 v[24:27], v[60:63], v[198:201], v[24:27]
	v_mfma_f32_16x16x32_bf16 v[20:23], v[76:79], v[198:201], v[20:23]
	v_mfma_f32_16x16x32_bf16 v[72:75], v[64:67], v[168:171], v[72:75]
	v_mfma_f32_16x16x32_bf16 v[68:71], v[80:83], v[168:171], v[68:71]
	v_mfma_f32_16x16x32_bf16 v[56:59], v[64:67], v[176:179], v[56:59]
	v_mfma_f32_16x16x32_bf16 v[52:55], v[80:83], v[176:179], v[52:55]
	v_mfma_f32_16x16x32_bf16 v[32:35], v[64:67], v[194:197], v[32:35]
	v_mfma_f32_16x16x32_bf16 v[28:31], v[80:83], v[194:197], v[28:31]
	v_mfma_f32_16x16x32_bf16 v[24:27], v[64:67], v[202:205], v[24:27]
	v_mfma_f32_16x16x32_bf16 v[20:23], v[80:83], v[202:205], v[20:23]
	s_setprio 0
	s_setprio 1
	v_mfma_f32_16x16x32_bf16 v[48:51], v[148:151], v[164:167], v[48:51]
	v_mfma_f32_16x16x32_bf16 v[44:47], v[156:159], v[164:167], v[44:47]
	v_mfma_f32_16x16x32_bf16 v[40:43], v[148:151], v[172:175], v[40:43]
	v_mfma_f32_16x16x32_bf16 v[36:39], v[156:159], v[172:175], v[36:39]
	v_mfma_f32_16x16x32_bf16 v[16:19], v[148:151], v[190:193], v[16:19]
	v_mfma_f32_16x16x32_bf16 v[12:15], v[156:159], v[190:193], v[12:15]
	v_mfma_f32_16x16x32_bf16 v[8:11], v[148:151], v[198:201], v[8:11]
	v_mfma_f32_16x16x32_bf16 v[4:7], v[156:159], v[198:201], v[4:7]
	v_mfma_f32_16x16x32_bf16 v[48:51], v[152:155], v[168:171], v[48:51]
	v_mfma_f32_16x16x32_bf16 v[44:47], v[160:163], v[168:171], v[44:47]
	v_mfma_f32_16x16x32_bf16 v[40:43], v[152:155], v[176:179], v[40:43]
	v_mfma_f32_16x16x32_bf16 v[36:39], v[160:163], v[176:179], v[36:39]
	v_mfma_f32_16x16x32_bf16 v[16:19], v[152:155], v[194:197], v[16:19]
	v_mfma_f32_16x16x32_bf16 v[12:15], v[160:163], v[194:197], v[12:15]
	v_mfma_f32_16x16x32_bf16 v[8:11], v[152:155], v[202:205], v[8:11]
	v_mfma_f32_16x16x32_bf16 v[4:7], v[160:163], v[202:205], v[4:7]
	s_setprio 0
	s_barrier
	s_add_i32 s60, 0, 0x18000
	s_add_i32 s61, 0, 0x1c000
	v_add_u32_e32 v80, s60, v212
	v_add_u32_e32 v160, s61, v212
	ds_read_b128 v[60:63], v80
	ds_read_b128 v[64:67], v80 offset:1024
	ds_read_b128 v[76:79], v80 offset:2048
	ds_read_b128 v[80:83], v80 offset:3072
	ds_read_b128 v[148:151], v160
	ds_read_b128 v[152:155], v160 offset:1024
	ds_read_b128 v[156:159], v160 offset:2048
	ds_read_b128 v[160:163], v160 offset:3072
	s_add_u32 s30, s46, 0x80000
	s_addc_u32 s31, s47, 0
	s_mov_b32 m0, s51
	v_lshl_add_u64 v[216:217], s[30:31], 0, v[180:181]
	ds_read_b128 v[164:167], v218 offset:32768
	ds_read_b128 v[168:171], v218 offset:33792
	ds_read_b128 v[172:175], v218 offset:34816
	ds_read_b128 v[176:179], v218 offset:35840
	ds_read_b128 v[190:193], v218 offset:36864
	ds_read_b128 v[194:197], v218 offset:37888
	ds_read_b128 v[198:201], v218 offset:38912
	ds_read_b128 v[202:205], v218 offset:39936
	global_load_lds_dwordx4 v[216:217], off
	v_lshl_add_u64 v[216:217], s[30:31], 0, v[182:183]
	s_mov_b32 m0, s52
	s_nop 0
	global_load_lds_dwordx4 v[216:217], off
	s_waitcnt vmcnt(8)
	s_waitcnt lgkmcnt(0)
	s_barrier
	s_setprio 1
	s_waitcnt lgkmcnt(0)
	v_mfma_f32_16x16x32_bf16 v[144:147], v[60:63], v[164:167], v[144:147]
	v_mfma_f32_16x16x32_bf16 v[140:143], v[76:79], v[164:167], v[140:143]
	v_mfma_f32_16x16x32_bf16 v[136:139], v[60:63], v[172:175], v[136:139]
	v_mfma_f32_16x16x32_bf16 v[132:135], v[76:79], v[172:175], v[132:135]
	v_mfma_f32_16x16x32_bf16 v[112:115], v[60:63], v[190:193], v[112:115]
	v_mfma_f32_16x16x32_bf16 v[108:111], v[76:79], v[190:193], v[108:111]
	v_mfma_f32_16x16x32_bf16 v[104:107], v[60:63], v[198:201], v[104:107]
	v_mfma_f32_16x16x32_bf16 v[100:103], v[76:79], v[198:201], v[100:103]
	v_mfma_f32_16x16x32_bf16 v[144:147], v[64:67], v[168:171], v[144:147]
	v_mfma_f32_16x16x32_bf16 v[140:143], v[80:83], v[168:171], v[140:143]
	v_mfma_f32_16x16x32_bf16 v[136:139], v[64:67], v[176:179], v[136:139]
	v_mfma_f32_16x16x32_bf16 v[132:135], v[80:83], v[176:179], v[132:135]
	v_mfma_f32_16x16x32_bf16 v[112:115], v[64:67], v[194:197], v[112:115]
	v_mfma_f32_16x16x32_bf16 v[108:111], v[80:83], v[194:197], v[108:111]
	v_mfma_f32_16x16x32_bf16 v[104:107], v[64:67], v[202:205], v[104:107]
	v_mfma_f32_16x16x32_bf16 v[100:103], v[80:83], v[202:205], v[100:103]
	s_setprio 0
	s_setprio 1
	v_mfma_f32_16x16x32_bf16 v[128:131], v[148:151], v[164:167], v[128:131]
	v_mfma_f32_16x16x32_bf16 v[124:127], v[156:159], v[164:167], v[124:127]
	v_mfma_f32_16x16x32_bf16 v[120:123], v[148:151], v[172:175], v[120:123]
	v_mfma_f32_16x16x32_bf16 v[116:119], v[156:159], v[172:175], v[116:119]
	v_mfma_f32_16x16x32_bf16 v[96:99], v[148:151], v[190:193], v[96:99]
	v_mfma_f32_16x16x32_bf16 v[92:95], v[156:159], v[190:193], v[92:95]
	v_mfma_f32_16x16x32_bf16 v[88:91], v[148:151], v[198:201], v[88:91]
	v_mfma_f32_16x16x32_bf16 v[84:87], v[156:159], v[198:201], v[84:87]
	v_mfma_f32_16x16x32_bf16 v[128:131], v[152:155], v[168:171], v[128:131]
	v_mfma_f32_16x16x32_bf16 v[124:127], v[160:163], v[168:171], v[124:127]
	v_mfma_f32_16x16x32_bf16 v[120:123], v[152:155], v[176:179], v[120:123]
	v_mfma_f32_16x16x32_bf16 v[116:119], v[160:163], v[176:179], v[116:119]
	v_mfma_f32_16x16x32_bf16 v[96:99], v[152:155], v[194:197], v[96:99]
	v_mfma_f32_16x16x32_bf16 v[92:95], v[160:163], v[194:197], v[92:95]
	v_mfma_f32_16x16x32_bf16 v[88:91], v[152:155], v[202:205], v[88:91]
	v_mfma_f32_16x16x32_bf16 v[84:87], v[160:163], v[202:205], v[84:87]
	s_setprio 0
	s_barrier
;     __device__ __forceinline__ void operator()(const f32x4 (&acc)[2][2][4][2], const Unit& u, int wr, int wc, int fr, int fq) const {
;         const int row0 = u.pm * BM + wr * 64 + fr; const int col0 = u.pn * BM + wc * 32 + 8 * fq;
;         const float* gp = gate + (size_t)((u.pm * BM) >> 12) * gstride + col0;
;         f32x4 gv[2][2];
; #pragma unroll
;         for (int bj = 0; bj < 2; ++bj)
; #pragma unroll
;             for (int n = 0; n < 2; ++n) gv[bj][n] = *(const f32x4*)(gp + bj * HALF + n * 4);
;         if (base_f32) { const float* bp = (const float*)base;
; #pragma unroll
;             for (int ai = 0; ai < 2; ++ai)
; #pragma unroll
;                 for (int m2 = 0; m2 < 2; ++m2) { f32x4 bs[2][2][2];
; #pragma unroll
;                     for (int mm = 0; mm < 2; ++mm) { const size_t off = (size_t)(row0 + ai * HALF + (2 * m2 + mm) * 16) * ldc + col0;
; #pragma unroll
;                         for (int bj = 0; bj < 2; ++bj)
; #pragma unroll
;                             for (int n = 0; n < 2; ++n) bs[mm][bj][n] = *(const f32x4*)(bp + off + bj * HALF + n * 4); }
; #pragma unroll
;                     for (int mm = 0; mm < 2; ++mm) { const size_t off = (size_t)(row0 + ai * HALF + (2 * m2 + mm) * 16) * ldc + col0;
; #pragma unroll
;                         for (int bj = 0; bj < 2; ++bj) { const f32x4 v0 = bs[mm][bj][0] + gv[bj][0] * acc[ai][bj][2 * m2 + mm][0], v1 = bs[mm][bj][1] + gv[bj][1] * acc[ai][bj][2 * m2 + mm][1];
;                             u32x4 w; w.x = cvt_pk_bf16(v0[0], v0[1]); w.y = cvt_pk_bf16(v0[2], v0[3]); w.z = cvt_pk_bf16(v1[0], v1[1]); w.w = cvt_pk_bf16(v1[2], v1[3]);
;                             *(u32x4*)(out + off + bj * HALF) = w; } }
;                     asm volatile("" ::: "memory"); }
;         } else { const bf16_t* bp = (const bf16_t*)base;
; #pragma unroll
;             for (int ai = 0; ai < 2; ++ai) { u32x4 bs[4][2];
; #pragma unroll
; template <class Epi, class Sched, bool ALIGN_EPI = false, bool SP2 = false>
; __device__ __forceinline__ void gemm_phase(PG8_LAS unsigned char* lds, const Gemm g, const Sched& S, const Epi& E) {
;     ...
;             PG8_LDA(At, 1, 1); PG8_STAGE(PG8_SB(1, 0), b3, voffB); PG8_STAGE(PG8_SB(1, 1), b3 + hstep, voffB); PG8_STAGE(PG8_SA(1, 0), a3, voffA);
;             PG8_WAIT_V(8); PG8_WAIT_L(0); PG8_BAR; PG8_MMA(1, 0, At, B0); PG8_MMA(1, 1, At, B1); PG8_BAR; PG8_SCHED;
	s_add_i32 s30, s60, s9
	v_lshl_add_u64 v[206:207], v[206:207], 0, s[28:29]
	s_mov_b32 m0, s30
	ds_read_b128 v[164:167], v218 offset:49152
	ds_read_b128 v[168:171], v218 offset:50176
	ds_read_b128 v[172:175], v218 offset:51200
	ds_read_b128 v[176:179], v218 offset:52224
	ds_read_b128 v[190:193], v218 offset:53248
	ds_read_b128 v[194:197], v218 offset:54272
	ds_read_b128 v[198:201], v218 offset:55296
	ds_read_b128 v[202:205], v218 offset:56320
	global_load_lds_dwordx4 v[206:207], off
	s_add_i32 m0, s30, 0x2000
	s_add_u32 s20, s20, 0x80080
	v_lshl_add_u64 v[206:207], v[208:209], 0, s[28:29]
	s_addc_u32 s21, s21, 0
	s_add_i32 s30, s61, s9
	global_load_lds_dwordx4 v[206:207], off
	v_lshl_add_u64 v[206:207], s[20:21], 0, v[2:3]
	s_mov_b32 m0, s30
	s_nop 0
	global_load_lds_dwordx4 v[206:207], off
	v_lshl_add_u64 v[206:207], s[20:21], 0, v[184:185]
	s_add_i32 m0, s30, 0x2000
	s_nop 0
	global_load_lds_dwordx4 v[206:207], off
	v_lshl_add_u64 v[206:207], v[210:211], 0, s[28:29]
	s_mov_b32 m0, s54
	s_nop 0
	global_load_lds_dwordx4 v[206:207], off
	v_lshl_add_u64 v[206:207], v[214:215], 0, s[28:29]
	s_mov_b32 m0, s55
	s_nop 0
	global_load_lds_dwordx4 v[206:207], off
	s_waitcnt vmcnt(8)
	s_waitcnt lgkmcnt(0)
	s_barrier
	s_setprio 1
	s_waitcnt lgkmcnt(0)
	v_mfma_f32_16x16x32_bf16 v[72:75], v[60:63], v[164:167], v[72:75]
	v_mfma_f32_16x16x32_bf16 v[68:71], v[76:79], v[164:167], v[68:71]
	v_mfma_f32_16x16x32_bf16 v[56:59], v[60:63], v[172:175], v[56:59]
	v_mfma_f32_16x16x32_bf16 v[52:55], v[76:79], v[172:175], v[52:55]
	v_mfma_f32_16x16x32_bf16 v[32:35], v[60:63], v[190:193], v[32:35]
	v_mfma_f32_16x16x32_bf16 v[28:31], v[76:79], v[190:193], v[28:31]
	v_mfma_f32_16x16x32_bf16 v[24:27], v[60:63], v[198:201], v[24:27]
	v_mfma_f32_16x16x32_bf16 v[20:23], v[76:79], v[198:201], v[20:23]
	v_mfma_f32_16x16x32_bf16 v[72:75], v[64:67], v[168:171], v[72:75]
	v_mfma_f32_16x16x32_bf16 v[68:71], v[80:83], v[168:171], v[68:71]
	v_mfma_f32_16x16x32_bf16 v[56:59], v[64:67], v[176:179], v[56:59]
	v_mfma_f32_16x16x32_bf16 v[52:55], v[80:83], v[176:179], v[52:55]
	v_mfma_f32_16x16x32_bf16 v[32:35], v[64:67], v[194:197], v[32:35]
	v_mfma_f32_16x16x32_bf16 v[28:31], v[80:83], v[194:197], v[28:31]
	v_mfma_f32_16x16x32_bf16 v[24:27], v[64:67], v[202:205], v[24:27]
	v_mfma_f32_16x16x32_bf16 v[20:23], v[80:83], v[202:205], v[20:23]
	s_setprio 0
	s_setprio 1
	v_mfma_f32_16x16x32_bf16 v[48:51], v[148:151], v[164:167], v[48:51]
	v_mfma_f32_16x16x32_bf16 v[44:47], v[156:159], v[164:167], v[44:47]
	v_mfma_f32_16x16x32_bf16 v[40:43], v[148:151], v[172:175], v[40:43]
	v_mfma_f32_16x16x32_bf16 v[36:39], v[156:159], v[172:175], v[36:39]
	v_mfma_f32_16x16x32_bf16 v[16:19], v[148:151], v[190:193], v[16:19]
	v_mfma_f32_16x16x32_bf16 v[12:15], v[156:159], v[190:193], v[12:15]
	v_mfma_f32_16x16x32_bf16 v[8:11], v[148:151], v[198:201], v[8:11]
	v_mfma_f32_16x16x32_bf16 v[4:7], v[156:159], v[198:201], v[4:7]
	v_mfma_f32_16x16x32_bf16 v[48:51], v[152:155], v[168:171], v[48:51]
	v_mfma_f32_16x16x32_bf16 v[44:47], v[160:163], v[168:171], v[44:47]
	v_mfma_f32_16x16x32_bf16 v[40:43], v[152:155], v[176:179], v[40:43]
	v_mfma_f32_16x16x32_bf16 v[36:39], v[160:163], v[176:179], v[36:39]
	v_mfma_f32_16x16x32_bf16 v[16:19], v[152:155], v[194:197], v[16:19]
	v_mfma_f32_16x16x32_bf16 v[12:15], v[160:163], v[194:197], v[12:15]
	v_mfma_f32_16x16x32_bf16 v[8:11], v[152:155], v[202:205], v[8:11]
	v_mfma_f32_16x16x32_bf16 v[4:7], v[160:163], v[202:205], v[4:7]
	s_setprio 0
	s_barrier
	s_add_i32 s59, s59, 2
	s_add_u32 s33, s33, 0x100
	s_addc_u32 s58, s58, 0
	s_add_u32 s44, s44, 0x100
	s_addc_u32 s45, s45, 0
	s_cmp_gt_u32 s59, 29
	s_cbranch_scc0 .LBB0_2046
	v_lshl_or_b32 v202, s4, 8, v213
	s_ashr_i32 s4, s42, 4
	s_mul_hi_i32 s13, s4, 0xc000
	s_mul_i32 s4, s4, 0xc000
	s_add_u32 s12, s18, s4
	s_addc_u32 s13, s53, s13
	v_ashrrev_i32_e32 v203, 31, v202
	v_lshl_add_u64 v[60:61], v[202:203], 2, s[12:13]
	flat_load_dwordx4 v[80:83], v[60:61]
	flat_load_dwordx4 v[76:79], v[60:61] offset:16
	flat_load_dwordx4 v[64:67], v[60:61] offset:512
	s_nop 0
	flat_load_dwordx4 v[60:63], v[60:61] offset:528
	v_lshl_add_u32 v192, s42, 8, v1
	v_ashrrev_i32_e32 v193, 31, v192
	v_or_b32_e32 v198, 16, v192
	v_or_b32_e32 v196, 32, v192
	v_or_b32_e32 v194, 48, v192
	v_lshlrev_b64 v[200:201], 11, v[192:193]
	s_and_b64 vcc, exec, s[16:17]
	v_lshlrev_b64 v[190:191], 1, v[202:203]
	v_ashrrev_i32_e32 v199, 31, v198
	v_ashrrev_i32_e32 v197, 31, v196
	v_ashrrev_i32_e32 v195, 31, v194
	s_cbranch_vccz .LBB0_2049
; __device__ __forceinline__ unsigned cvt_pk_bf16(float lo, float hi) { unsigned r; asm volatile("v_cvt_pk_bf16_f32 %0, %1, %2" : "=v"(r) : "v"(lo), "v"(hi)); return r; }
;     __device__ __forceinline__ void operator()(const f32x4 (&acc)[2][2][4][2], const Unit& u, int wr, int wc, int fr, int fq) const {
;     ...
;             for (int ai = 0; ai < 2; ++ai) { u32x4 bs[4][2];
; #pragma unroll
;                 for (int m = 0; m < 4; ++m) { const size_t off = (size_t)(row0 + ai * HALF + m * 16) * ldc + col0;
; #pragma unroll
;                     for (int bj = 0; bj < 2; ++bj) bs[m][bj] = *(const u32x4*)(bp + off + bj * HALF); }
; #pragma unroll
;                 for (int m = 0; m < 4; ++m) { const size_t off = (size_t)(row0 + ai * HALF + m * 16) * ldc + col0;
; #pragma unroll
;                     for (int bj = 0; bj < 2; ++bj) { const u32x4 r = bs[m][bj]; const f32x4 a0 = acc[ai][bj][m][0], a1 = acc[ai][bj][m][1];
;                         u32x4 w;
;                         w.x = cvt_pk_bf16(__builtin_bit_cast(float, r.x << 16) + gv[bj][0][0] * a0[0], __builtin_bit_cast(float, r.x & 0xffff0000u) + gv[bj][0][1] * a0[1]);
;                         w.y = cvt_pk_bf16(__builtin_bit_cast(float, r.y << 16) + gv[bj][0][2] * a0[2], __builtin_bit_cast(float, r.y & 0xffff0000u) + gv[bj][0][3] * a0[3]);
;                         w.z = cvt_pk_bf16(__builtin_bit_cast(float, r.z << 16) + gv[bj][1][0] * a1[0], __builtin_bit_cast(float, r.z & 0xffff0000u) + gv[bj][1][1] * a1[1]);
;                         w.w = cvt_pk_bf16(__builtin_bit_cast(float, r.w << 16) + gv[bj][1][2] * a1[2], __builtin_bit_cast(float, r.w & 0xffff0000u) + gv[bj][1][3] * a1[3]);
;                         *(u32x4*)(out + off + bj * HALF) = w; } }
	v_lshl_add_u64 v[204:205], s[26:27], 0, v[190:191]
	v_lshlrev_b64 v[156:157], 1, v[200:201]
	v_lshl_add_u64 v[148:149], v[204:205], 0, v[156:157]
	v_lshlrev_b64 v[152:153], 12, v[198:199]
	flat_load_dwordx4 v[172:175], v[148:149]
	flat_load_dwordx4 v[168:171], v[148:149] offset:256
	v_lshl_add_u64 v[148:149], v[204:205], 0, v[152:153]
	flat_load_dwordx4 v[164:167], v[148:149]
	s_nop 0
	flat_load_dwordx4 v[148:151], v[148:149] offset:256
	v_lshlrev_b64 v[208:209], 12, v[196:197]
	v_lshlrev_b64 v[206:207], 12, v[194:195]
	v_lshl_add_u64 v[154:155], v[204:205], 0, v[208:209]
	v_lshl_add_u64 v[210:211], v[204:205], 0, v[206:207]
	v_lshl_add_u64 v[214:215], s[14:15], 0, v[156:157]
	v_lshl_add_u64 v[216:217], s[14:15], 0, v[152:153]
	flat_load_dwordx4 v[176:179], v[154:155]
	flat_load_dwordx4 v[160:163], v[154:155] offset:256
	flat_load_dwordx4 v[156:159], v[210:211]
	s_nop 0
	flat_load_dwordx4 v[152:155], v[210:211] offset:256
	v_lshlrev_b64 v[244:245], 12, v[192:193]
	v_lshl_add_u64 v[244:245], v[204:205], 0, v[244:245]
	s_mov_b64 s[12:13], 0x80000
	v_lshl_add_u64 v[246:247], v[244:245], 0, s[12:13]
	global_load_dwordx4 v[248:251], v[246:247], off
	global_load_dwordx4 v[248:251], v[246:247], off offset:256
	s_mov_b64 s[12:13], 0x90000
	v_lshl_add_u64 v[246:247], v[244:245], 0, s[12:13]
	global_load_dwordx4 v[248:251], v[246:247], off
	global_load_dwordx4 v[248:251], v[246:247], off offset:256
	s_mov_b64 s[12:13], 0xa0000
	v_lshl_add_u64 v[246:247], v[244:245], 0, s[12:13]
	global_load_dwordx4 v[248:251], v[246:247], off
	global_load_dwordx4 v[248:251], v[246:247], off offset:256
	s_mov_b64 s[12:13], 0xb0000
	v_lshl_add_u64 v[246:247], v[244:245], 0, s[12:13]
	global_load_dwordx4 v[248:251], v[246:247], off
	global_load_dwordx4 v[248:251], v[246:247], off offset:256
	v_lshl_add_u64 v[210:211], v[216:217], 0, v[190:191]
	v_lshl_add_u64 v[214:215], v[214:215], 0, v[190:191]
	s_mov_b64 s[12:13], 0x80000
	s_waitcnt vmcnt(0) lgkmcnt(0)
	v_lshlrev_b32_e32 v216, 16, v172
	v_and_b32_e32 v172, 0xffff0000, v172
	v_lshlrev_b32_e32 v217, 16, v173
	v_and_b32_e32 v173, 0xffff0000, v173
	v_lshlrev_b32_e32 v219, 16, v174
	v_and_b32_e32 v174, 0xffff0000, v174
	v_lshlrev_b32_e32 v220, 16, v175
	v_and_b32_e32 v175, 0xffff0000, v175
	v_lshlrev_b32_e32 v221, 16, v168
	v_and_b32_e32 v168, 0xffff0000, v168
	v_lshlrev_b32_e32 v225, 16, v164
	v_and_b32_e32 v226, 0xffff0000, v164
	v_fmac_f32_e32 v216, v144, v80
	v_fmac_f32_e32 v172, v145, v81
	v_cvt_pk_bf16_f32 v164, v216, v172
	v_lshlrev_b32_e32 v222, 16, v169
	v_and_b32_e32 v169, 0xffff0000, v169
	v_lshlrev_b32_e32 v223, 16, v170
	v_and_b32_e32 v170, 0xffff0000, v170
	v_lshlrev_b32_e32 v224, 16, v171
	v_and_b32_e32 v171, 0xffff0000, v171
	v_lshlrev_b32_e32 v227, 16, v165
	v_and_b32_e32 v229, 0xffff0000, v165
	v_lshlrev_b32_e32 v232, 16, v166
	v_and_b32_e32 v233, 0xffff0000, v166
	v_lshlrev_b32_e32 v240, 16, v167
	v_and_b32_e32 v241, 0xffff0000, v167
	v_fmac_f32_e32 v217, v146, v82
	v_fmac_f32_e32 v173, v147, v83
	v_fmac_f32_e32 v219, v140, v76
	v_fmac_f32_e32 v174, v141, v77
	v_fmac_f32_e32 v220, v142, v78
	v_fmac_f32_e32 v175, v143, v79
	v_fmac_f32_e32 v221, v128, v64
	v_fmac_f32_e32 v168, v129, v65
	v_cvt_pk_bf16_f32 v165, v217, v173
	v_cvt_pk_bf16_f32 v166, v219, v174
	v_cvt_pk_bf16_f32 v167, v220, v175
	flat_store_dwordx4 v[214:215], v[164:167]
	v_fmac_f32_e32 v222, v130, v66
	v_fmac_f32_e32 v169, v131, v67
	v_cvt_pk_bf16_f32 v164, v221, v168
	v_fmac_f32_e32 v223, v124, v60
	v_fmac_f32_e32 v170, v125, v61
	v_fmac_f32_e32 v224, v126, v62
	v_fmac_f32_e32 v171, v127, v63
	v_fmac_f32_e32 v225, v136, v80
	v_fmac_f32_e32 v226, v137, v81
	v_cvt_pk_bf16_f32 v165, v222, v169
	v_cvt_pk_bf16_f32 v166, v223, v170
	v_cvt_pk_bf16_f32 v167, v224, v171
	flat_store_dwordx4 v[214:215], v[164:167] offset:256
	v_lshlrev_b32_e32 v242, 16, v148
	v_and_b32_e32 v148, 0xffff0000, v148
	v_cvt_pk_bf16_f32 v164, v225, v226
	v_fmac_f32_e32 v227, v138, v82
	v_fmac_f32_e32 v229, v139, v83
	v_fmac_f32_e32 v232, v132, v76
	v_fmac_f32_e32 v233, v133, v77
	v_fmac_f32_e32 v240, v134, v78
	v_fmac_f32_e32 v241, v135, v79
	v_cvt_pk_bf16_f32 v165, v227, v229
	v_cvt_pk_bf16_f32 v166, v232, v233
	v_cvt_pk_bf16_f32 v167, v240, v241
	flat_store_dwordx4 v[210:211], v[164:167]
	v_fmac_f32_e32 v148, v121, v65
	v_fmac_f32_e32 v242, v120, v64
	v_lshlrev_b32_e32 v164, 16, v149
	v_and_b32_e32 v149, 0xffff0000, v149
	v_fmac_f32_e32 v164, v122, v66
	v_fmac_f32_e32 v149, v123, v67
	v_cvt_pk_bf16_f32 v148, v242, v148
	v_cvt_pk_bf16_f32 v149, v164, v149
	v_lshlrev_b32_e32 v164, 16, v150
	v_and_b32_e32 v150, 0xffff0000, v150
	v_fmac_f32_e32 v164, v116, v60
	v_fmac_f32_e32 v150, v117, v61
	v_cvt_pk_bf16_f32 v150, v164, v150
	v_lshlrev_b32_e32 v164, 16, v151
	v_and_b32_e32 v151, 0xffff0000, v151
	v_fmac_f32_e32 v151, v119, v63
	v_fmac_f32_e32 v164, v118, v62
	v_cvt_pk_bf16_f32 v151, v164, v151
	flat_store_dwordx4 v[210:211], v[148:151] offset:256
	v_and_b32_e32 v164, 0xffff0000, v179
	v_fmac_f32_e32 v164, v111, v79
	v_lshlrev_b32_e32 v148, 16, v176
	v_and_b32_e32 v149, 0xffff0000, v176
	v_fmac_f32_e32 v148, v112, v80
	v_fmac_f32_e32 v149, v113, v81
	v_cvt_pk_bf16_f32 v148, v148, v149
	v_lshlrev_b32_e32 v149, 16, v177
	v_and_b32_e32 v150, 0xffff0000, v177
	v_fmac_f32_e32 v149, v114, v82
	v_fmac_f32_e32 v150, v115, v83
	v_cvt_pk_bf16_f32 v149, v149, v150
	v_lshlrev_b32_e32 v150, 16, v178
	v_and_b32_e32 v151, 0xffff0000, v178
	v_fmac_f32_e32 v150, v108, v76
	v_fmac_f32_e32 v151, v109, v77
	v_cvt_pk_bf16_f32 v150, v150, v151
	v_lshlrev_b32_e32 v151, 16, v179
	v_fmac_f32_e32 v151, v110, v78
	v_cvt_pk_bf16_f32 v151, v151, v164
	v_lshl_add_u64 v[164:165], s[14:15], 0, v[208:209]
; __device__ __forceinline__ unsigned cvt_pk_bf16(float lo, float hi) { unsigned r; asm volatile("v_cvt_pk_bf16_f32 %0, %1, %2" : "=v"(r) : "v"(lo), "v"(hi)); return r; }
;     __device__ __forceinline__ void operator()(const f32x4 (&acc)[2][2][4][2], const Unit& u, int wr, int wc, int fr, int fq) const {
;     ...
;             for (int ai = 0; ai < 2; ++ai) { u32x4 bs[4][2];
; #pragma unroll
;                 for (int m = 0; m < 4; ++m) { const size_t off = (size_t)(row0 + ai * HALF + m * 16) * ldc + col0;
; #pragma unroll
;                     for (int bj = 0; bj < 2; ++bj) bs[m][bj] = *(const u32x4*)(bp + off + bj * HALF); }
; #pragma unroll
;                 for (int m = 0; m < 4; ++m) { const size_t off = (size_t)(row0 + ai * HALF + m * 16) * ldc + col0;
; #pragma unroll
;                     for (int bj = 0; bj < 2; ++bj) { const u32x4 r = bs[m][bj]; const f32x4 a0 = acc[ai][bj][m][0], a1 = acc[ai][bj][m][1];
;                         u32x4 w;
;                         w.x = cvt_pk_bf16(__builtin_bit_cast(float, r.x << 16) + gv[bj][0][0] * a0[0], __builtin_bit_cast(float, r.x & 0xffff0000u) + gv[bj][0][1] * a0[1]);
;                         w.y = cvt_pk_bf16(__builtin_bit_cast(float, r.y << 16) + gv[bj][0][2] * a0[2], __builtin_bit_cast(float, r.y & 0xffff0000u) + gv[bj][0][3] * a0[3]);
;                         w.z = cvt_pk_bf16(__builtin_bit_cast(float, r.z << 16) + gv[bj][1][0] * a1[0], __builtin_bit_cast(float, r.z & 0xffff0000u) + gv[bj][1][1] * a1[1]);
;                         w.w = cvt_pk_bf16(__builtin_bit_cast(float, r.w << 16) + gv[bj][1][2] * a1[2], __builtin_bit_cast(float, r.w & 0xffff0000u) + gv[bj][1][3] * a1[3]);
;                         *(u32x4*)(out + off + bj * HALF) = w; } }
	v_lshl_add_u64 v[164:165], v[164:165], 0, v[190:191]
	flat_store_dwordx4 v[164:165], v[148:151]
	s_nop 1
	v_lshlrev_b32_e32 v148, 16, v160
	v_and_b32_e32 v149, 0xffff0000, v160
	v_fmac_f32_e32 v148, v96, v64
	v_fmac_f32_e32 v149, v97, v65
	v_cvt_pk_bf16_f32 v148, v148, v149
	v_lshlrev_b32_e32 v149, 16, v161
	v_and_b32_e32 v150, 0xffff0000, v161
	v_fmac_f32_e32 v149, v98, v66
	v_fmac_f32_e32 v150, v99, v67
	v_cvt_pk_bf16_f32 v149, v149, v150
	v_lshlrev_b32_e32 v150, 16, v162
	v_and_b32_e32 v151, 0xffff0000, v162
	v_fmac_f32_e32 v150, v92, v60
	v_fmac_f32_e32 v151, v93, v61
	v_cvt_pk_bf16_f32 v150, v150, v151
	v_lshlrev_b32_e32 v151, 16, v163
	v_fmac_f32_e32 v151, v94, v62
	v_and_b32_e32 v160, 0xffff0000, v163
	v_fmac_f32_e32 v160, v95, v63
	v_cvt_pk_bf16_f32 v151, v151, v160
	flat_store_dwordx4 v[164:165], v[148:151] offset:256
	s_nop 1
	v_lshlrev_b32_e32 v148, 16, v156
	v_and_b32_e32 v149, 0xffff0000, v156
	v_fmac_f32_e32 v148, v104, v80
	v_fmac_f32_e32 v149, v105, v81
	v_cvt_pk_bf16_f32 v148, v148, v149
	v_lshlrev_b32_e32 v149, 16, v157
	v_and_b32_e32 v150, 0xffff0000, v157
	v_fmac_f32_e32 v149, v106, v82
	v_fmac_f32_e32 v150, v107, v83
	v_cvt_pk_bf16_f32 v149, v149, v150
	v_lshlrev_b32_e32 v150, 16, v158
	v_and_b32_e32 v151, 0xffff0000, v158
	v_fmac_f32_e32 v150, v100, v76
	v_fmac_f32_e32 v151, v101, v77
	v_cvt_pk_bf16_f32 v150, v150, v151
	v_lshlrev_b32_e32 v151, 16, v159
	v_and_b32_e32 v156, 0xffff0000, v159
	v_fmac_f32_e32 v151, v102, v78
	v_fmac_f32_e32 v156, v103, v79
	v_cvt_pk_bf16_f32 v151, v151, v156
	v_lshl_add_u64 v[156:157], s[14:15], 0, v[206:207]
	v_lshl_add_u64 v[156:157], v[156:157], 0, v[190:191]
	flat_store_dwordx4 v[156:157], v[148:151]
	s_nop 1
	v_lshlrev_b32_e32 v148, 16, v152
	v_and_b32_e32 v149, 0xffff0000, v152
	v_fmac_f32_e32 v148, v88, v64
	v_fmac_f32_e32 v149, v89, v65
	v_cvt_pk_bf16_f32 v148, v148, v149
	v_lshlrev_b32_e32 v149, 16, v153
	v_and_b32_e32 v150, 0xffff0000, v153
	v_fmac_f32_e32 v149, v90, v66
	v_fmac_f32_e32 v150, v91, v67
	v_cvt_pk_bf16_f32 v149, v149, v150
	v_lshlrev_b32_e32 v150, 16, v154
	v_and_b32_e32 v151, 0xffff0000, v154
	v_fmac_f32_e32 v150, v84, v60
	v_fmac_f32_e32 v151, v85, v61
	v_cvt_pk_bf16_f32 v150, v150, v151
	v_lshlrev_b32_e32 v151, 16, v155
	v_fmac_f32_e32 v151, v86, v62
	v_and_b32_e32 v152, 0xffff0000, v155
	v_fmac_f32_e32 v152, v87, v63
	v_cvt_pk_bf16_f32 v151, v151, v152
	flat_store_dwordx4 v[156:157], v[148:151] offset:256
	s_nop 1
	v_lshlrev_b64 v[148:149], 12, v[192:193]
	v_lshl_add_u64 v[206:207], v[148:149], 0, s[12:13]
	v_lshl_add_u64 v[150:151], v[204:205], 0, v[206:207]
	flat_load_dwordx4 v[152:155], v[150:151]
	flat_load_dwordx4 v[156:159], v[150:151] offset:256
	s_mov_b64 s[12:13], 0x90000
	v_lshl_add_u64 v[208:209], v[148:149], 0, s[12:13]
	v_lshl_add_u64 v[150:151], v[204:205], 0, v[208:209]
	flat_load_dwordx4 v[160:163], v[150:151]
	flat_load_dwordx4 v[164:167], v[150:151] offset:256
	s_mov_b64 s[12:13], 0xa0000
	v_lshl_add_u64 v[210:211], v[148:149], 0, s[12:13]
	v_lshl_add_u64 v[150:151], v[204:205], 0, v[210:211]
	flat_load_dwordx4 v[168:171], v[150:151]
	flat_load_dwordx4 v[172:175], v[150:151] offset:256
	s_mov_b64 s[12:13], 0xb0000
	v_lshl_add_u64 v[214:215], v[148:149], 0, s[12:13]
	v_lshl_add_u64 v[148:149], v[204:205], 0, v[214:215]
	flat_load_dwordx4 v[176:179], v[148:149]
	s_nop 0
	flat_load_dwordx4 v[148:151], v[148:149] offset:256
	v_lshl_add_u64 v[204:205], s[14:15], 0, v[206:207]
	v_lshl_add_u64 v[204:205], v[204:205], 0, v[190:191]
	s_waitcnt vmcnt(0) lgkmcnt(0)
; __device__ __forceinline__ unsigned cvt_pk_bf16(float lo, float hi) { unsigned r; asm volatile("v_cvt_pk_bf16_f32 %0, %1, %2" : "=v"(r) : "v"(lo), "v"(hi)); return r; }
;     __device__ __forceinline__ void operator()(const f32x4 (&acc)[2][2][4][2], const Unit& u, int wr, int wc, int fr, int fq) const {
;     ...
;                 for (int m = 0; m < 4; ++m) { const size_t off = (size_t)(row0 + ai * HALF + m * 16) * ldc + col0;
; #pragma unroll
;                     for (int bj = 0; bj < 2; ++bj) { const u32x4 r = bs[m][bj]; const f32x4 a0 = acc[ai][bj][m][0], a1 = acc[ai][bj][m][1];
;                         u32x4 w;
;                         w.x = cvt_pk_bf16(__builtin_bit_cast(float, r.x << 16) + gv[bj][0][0] * a0[0], __builtin_bit_cast(float, r.x & 0xffff0000u) + gv[bj][0][1] * a0[1]);
;                         w.y = cvt_pk_bf16(__builtin_bit_cast(float, r.y << 16) + gv[bj][0][2] * a0[2], __builtin_bit_cast(float, r.y & 0xffff0000u) + gv[bj][0][3] * a0[3]);
;                         w.z = cvt_pk_bf16(__builtin_bit_cast(float, r.z << 16) + gv[bj][1][0] * a1[0], __builtin_bit_cast(float, r.z & 0xffff0000u) + gv[bj][1][1] * a1[1]);
;                         w.w = cvt_pk_bf16(__builtin_bit_cast(float, r.w << 16) + gv[bj][1][2] * a1[2], __builtin_bit_cast(float, r.w & 0xffff0000u) + gv[bj][1][3] * a1[3]);
;                         *(u32x4*)(out + off + bj * HALF) = w; } }
	v_lshlrev_b32_e32 v193, 16, v152
	v_and_b32_e32 v152, 0xffff0000, v152
	v_fmac_f32_e32 v193, v72, v80
	v_fmac_f32_e32 v152, v73, v81
	v_cvt_pk_bf16_f32 v152, v193, v152
	v_lshlrev_b32_e32 v193, 16, v153
	v_and_b32_e32 v153, 0xffff0000, v153
	v_fmac_f32_e32 v193, v74, v82
	v_fmac_f32_e32 v153, v75, v83
	v_cvt_pk_bf16_f32 v153, v193, v153
	v_lshlrev_b32_e32 v193, 16, v154
	v_and_b32_e32 v154, 0xffff0000, v154
	v_fmac_f32_e32 v193, v68, v76
	v_fmac_f32_e32 v154, v69, v77
	v_cvt_pk_bf16_f32 v154, v193, v154
	v_lshlrev_b32_e32 v193, 16, v155
	v_and_b32_e32 v155, 0xffff0000, v155
	v_fmac_f32_e32 v155, v71, v79
	v_fmac_f32_e32 v193, v70, v78
	v_cvt_pk_bf16_f32 v155, v193, v155
	flat_store_dwordx4 v[204:205], v[152:155]
	s_nop 1
	v_lshlrev_b32_e32 v152, 16, v156
	v_and_b32_e32 v153, 0xffff0000, v156
	v_fmac_f32_e32 v152, v48, v64
	v_fmac_f32_e32 v153, v49, v65
	v_cvt_pk_bf16_f32 v152, v152, v153
	v_lshlrev_b32_e32 v153, 16, v157
	v_and_b32_e32 v154, 0xffff0000, v157
	v_fmac_f32_e32 v153, v50, v66
	v_fmac_f32_e32 v154, v51, v67
	v_cvt_pk_bf16_f32 v153, v153, v154
	v_lshlrev_b32_e32 v154, 16, v158
	v_and_b32_e32 v155, 0xffff0000, v158
	v_fmac_f32_e32 v154, v44, v60
	v_fmac_f32_e32 v155, v45, v61
	v_cvt_pk_bf16_f32 v154, v154, v155
	v_lshlrev_b32_e32 v155, 16, v159
	v_fmac_f32_e32 v155, v46, v62
	v_and_b32_e32 v156, 0xffff0000, v159
	v_fmac_f32_e32 v156, v47, v63
	v_cvt_pk_bf16_f32 v155, v155, v156
	flat_store_dwordx4 v[204:205], v[152:155] offset:256
	v_and_b32_e32 v156, 0xffff0000, v163
	v_fmac_f32_e32 v156, v55, v79
	v_lshlrev_b32_e32 v152, 16, v160
	v_and_b32_e32 v153, 0xffff0000, v160
	v_fmac_f32_e32 v152, v56, v80
	v_fmac_f32_e32 v153, v57, v81
	v_cvt_pk_bf16_f32 v152, v152, v153
	v_lshlrev_b32_e32 v153, 16, v161
	v_and_b32_e32 v154, 0xffff0000, v161
	v_fmac_f32_e32 v153, v58, v82
	v_fmac_f32_e32 v154, v59, v83
	v_cvt_pk_bf16_f32 v153, v153, v154
	v_lshlrev_b32_e32 v154, 16, v162
	v_and_b32_e32 v155, 0xffff0000, v162
	v_fmac_f32_e32 v154, v52, v76
	v_fmac_f32_e32 v155, v53, v77
	v_cvt_pk_bf16_f32 v154, v154, v155
	v_lshlrev_b32_e32 v155, 16, v163
	v_fmac_f32_e32 v155, v54, v78
	v_cvt_pk_bf16_f32 v155, v155, v156
	v_lshl_add_u64 v[156:157], s[14:15], 0, v[208:209]
	v_lshl_add_u64 v[156:157], v[156:157], 0, v[190:191]
	flat_store_dwordx4 v[156:157], v[152:155]
	v_and_b32_e32 v158, 0xffff0000, v167
	v_fmac_f32_e32 v158, v39, v63
	v_lshlrev_b32_e32 v152, 16, v164
	v_and_b32_e32 v153, 0xffff0000, v164
	v_fmac_f32_e32 v152, v40, v64
	v_fmac_f32_e32 v153, v41, v65
	v_cvt_pk_bf16_f32 v152, v152, v153
	v_lshlrev_b32_e32 v153, 16, v165
	v_and_b32_e32 v154, 0xffff0000, v165
	v_fmac_f32_e32 v153, v42, v66
	v_fmac_f32_e32 v154, v43, v67
	v_cvt_pk_bf16_f32 v153, v153, v154
	v_lshlrev_b32_e32 v154, 16, v166
	v_and_b32_e32 v155, 0xffff0000, v166
	v_fmac_f32_e32 v154, v36, v60
	v_fmac_f32_e32 v155, v37, v61
	v_cvt_pk_bf16_f32 v154, v154, v155
	v_lshlrev_b32_e32 v155, 16, v167
	v_fmac_f32_e32 v155, v38, v62
	v_cvt_pk_bf16_f32 v155, v155, v158
	flat_store_dwordx4 v[156:157], v[152:155] offset:256
	v_and_b32_e32 v156, 0xffff0000, v171
	v_fmac_f32_e32 v156, v31, v79
	v_lshlrev_b32_e32 v152, 16, v168
	v_and_b32_e32 v153, 0xffff0000, v168
	v_fmac_f32_e32 v152, v32, v80
	v_fmac_f32_e32 v153, v33, v81
	v_cvt_pk_bf16_f32 v152, v152, v153
	v_lshlrev_b32_e32 v153, 16, v169
	v_and_b32_e32 v154, 0xffff0000, v169
	v_fmac_f32_e32 v153, v34, v82
	v_fmac_f32_e32 v154, v35, v83
	v_cvt_pk_bf16_f32 v153, v153, v154
	v_lshlrev_b32_e32 v154, 16, v170
	v_and_b32_e32 v155, 0xffff0000, v170
	v_fmac_f32_e32 v154, v28, v76
	v_fmac_f32_e32 v155, v29, v77
	v_cvt_pk_bf16_f32 v154, v154, v155
	v_lshlrev_b32_e32 v155, 16, v171
	v_fmac_f32_e32 v155, v30, v78
	v_cvt_pk_bf16_f32 v155, v155, v156
	v_lshl_add_u64 v[156:157], s[14:15], 0, v[210:211]
	v_lshl_add_u64 v[156:157], v[156:157], 0, v[190:191]
	flat_store_dwordx4 v[156:157], v[152:155]
	v_and_b32_e32 v158, 0xffff0000, v175
	v_fmac_f32_e32 v158, v15, v63
	v_lshlrev_b32_e32 v152, 16, v172
	v_and_b32_e32 v153, 0xffff0000, v172
	v_fmac_f32_e32 v152, v16, v64
	v_fmac_f32_e32 v153, v17, v65
	v_cvt_pk_bf16_f32 v152, v152, v153
	v_lshlrev_b32_e32 v153, 16, v173
	v_and_b32_e32 v154, 0xffff0000, v173
	v_fmac_f32_e32 v153, v18, v66
	v_fmac_f32_e32 v154, v19, v67
	v_cvt_pk_bf16_f32 v153, v153, v154
	v_lshlrev_b32_e32 v154, 16, v174
	v_and_b32_e32 v155, 0xffff0000, v174
	v_fmac_f32_e32 v154, v12, v60
	v_fmac_f32_e32 v155, v13, v61
	v_cvt_pk_bf16_f32 v154, v154, v155
	v_lshlrev_b32_e32 v155, 16, v175
	v_fmac_f32_e32 v155, v14, v62
	v_cvt_pk_bf16_f32 v155, v155, v158
	flat_store_dwordx4 v[156:157], v[152:155] offset:256
	v_and_b32_e32 v156, 0xffff0000, v179
	v_fmac_f32_e32 v156, v23, v79
	v_lshlrev_b32_e32 v152, 16, v176
	v_and_b32_e32 v153, 0xffff0000, v176
	v_fmac_f32_e32 v152, v24, v80
	v_fmac_f32_e32 v153, v25, v81
	v_cvt_pk_bf16_f32 v152, v152, v153
	v_lshlrev_b32_e32 v153, 16, v177
	v_and_b32_e32 v154, 0xffff0000, v177
	v_fmac_f32_e32 v153, v26, v82
	v_fmac_f32_e32 v154, v27, v83
	v_cvt_pk_bf16_f32 v153, v153, v154
	v_lshlrev_b32_e32 v154, 16, v178
	v_and_b32_e32 v155, 0xffff0000, v178
	v_fmac_f32_e32 v154, v20, v76
	v_fmac_f32_e32 v155, v21, v77
	v_cvt_pk_bf16_f32 v154, v154, v155
	v_lshlrev_b32_e32 v155, 16, v179
	v_fmac_f32_e32 v155, v22, v78
	v_cvt_pk_bf16_f32 v155, v155, v156
	v_lshl_add_u64 v[156:157], s[14:15], 0, v[214:215]
	v_lshl_add_u64 v[156:157], v[156:157], 0, v[190:191]
	flat_store_dwordx4 v[156:157], v[152:155]
	s_nop 1
	v_lshlrev_b32_e32 v152, 16, v148
	v_and_b32_e32 v148, 0xffff0000, v148
	v_fmac_f32_e32 v152, v8, v64
	v_fmac_f32_e32 v148, v9, v65
	v_cvt_pk_bf16_f32 v148, v152, v148
	v_lshlrev_b32_e32 v152, 16, v149
	v_and_b32_e32 v149, 0xffff0000, v149
	v_fmac_f32_e32 v152, v10, v66
	v_fmac_f32_e32 v149, v11, v67
	v_cvt_pk_bf16_f32 v149, v152, v149
	v_lshlrev_b32_e32 v152, 16, v150
	v_and_b32_e32 v150, 0xffff0000, v150
	v_fmac_f32_e32 v152, v4, v60
	v_fmac_f32_e32 v150, v5, v61
	v_cvt_pk_bf16_f32 v150, v152, v150
	v_lshlrev_b32_e32 v152, 16, v151
	v_and_b32_e32 v151, 0xffff0000, v151
	v_fmac_f32_e32 v151, v7, v63
	v_fmac_f32_e32 v152, v6, v62
	v_cvt_pk_bf16_f32 v151, v152, v151
	flat_store_dwordx4 v[156:157], v[148:151] offset:256
	s_cbranch_execnz .LBB0_2038
	s_branch .LBB0_2050

; #define PG8_STAGE(bufoff, gbase, voff) do { _Pragma("unroll") for (int _i = 0; _i < 2; ++_i) \
;         __builtin_amdgcn_global_load_lds((const unsigned*)((const char*)(gbase) + (voff)[_i]), (PG8_LAS unsigned*)(lds + (bufoff) + ldsw + _i * 8192), 16, 0, 0); } while (0)
; #define PG8_LDA(dst, b, h) do { _Pragma("unroll") for (int m = 0; m < 4; ++m) _Pragma("unroll") for (int k = 0; k < 2; ++k) dst[m][k] = *(const PG8_LAS bf16x8*)(lds + PG8_SA(b, h) + aoff + m * 2048 + k * 1024); } while (0)
; #define PG8_LDB(dst, b, h) do { _Pragma("unroll") for (int n = 0; n < 2; ++n) _Pragma("unroll") for (int k = 0; k < 2; ++k) dst[n][k] = *(const PG8_LAS bf16x8*)(lds + PG8_SB(b, h) + boff + n * 2048 + k * 1024); } while (0)
; #define PG8_WAIT_V(n) asm volatile("s_waitcnt vmcnt(" #n ")" ::: "memory")
; #define PG8_WAIT_L(n) asm volatile("s_waitcnt lgkmcnt(" #n ")" ::: "memory")
; #define PG8_BAR __builtin_amdgcn_s_barrier()
; #define PG8_SCHED __builtin_amdgcn_sched_barrier(0)
; template <class Epi, class Sched, bool ALIGN_EPI = false, bool SP2 = false>
; __device__ __forceinline__ void gemm_phase(PG8_LAS unsigned char* lds, const Gemm g, const Sched& S, const Epi& E) {
;     ...
;         const bool has_next = S.next(ui + 1, nxt);
;         const char* nA = has_next ? (const char*)g.A + (size_t)nxt.pm * tstep : cA; const char* nB = has_next ? (const char*)g.Bt + (size_t)nxt.pn * tstep : cB;
;         for (int t = 0; t < nt; t += 2) {
;             const bool last = (t == nt - 2);
;             const char* a1 = cA + (size_t)(t + 1) * kstep;
;             const char* a2 = last ? nA : cA + (size_t)(t + 2) * kstep; const char* b2 = last ? nB : cB + (size_t)(t + 2) * kstep;
;             const char* a3 = a2 + kstep; const char* b3 = b2 + kstep;
;             if (last && has_next) S.a_ready(nxt);
;             if constexpr (SP2) {
;             PG8_LDB(B0, 0, 0); PG8_LDB(B1, 0, 1); PG8_SCHED; PG8_LDA(At, 0, 0); PG8_STAGE(PG8_SA(1, 1), a1 + hstep, voffA);
;             PG8_WAIT_V(8); PG8_WAIT_L(0); PG8_BAR; PG8_MMA(0, 0, At, B0); PG8_MMA(0, 1, At, B1); PG8_BAR; PG8_SCHED;
;             PG8_LDA(At, 0, 1); PG8_STAGE(PG8_SB(0, 0), b2, voffB); PG8_STAGE(PG8_SB(0, 1), b2 + hstep, voffB); PG8_STAGE(PG8_SA(0, 0), a2, voffA);
;             PG8_WAIT_V(8); PG8_WAIT_L(0); PG8_BAR; PG8_MMA(1, 0, At, B0); PG8_MMA(1, 1, At, B1); PG8_BAR; PG8_SCHED;
.LBB0_2238:
	s_add_u32 s24, s20, 0x100
	s_addc_u32 s25, s21, 0
	s_add_i32 s30, 0, 0x10000
	s_cmpk_eq_i32 s42, 0x54
	s_cselect_b32 s37, s17, s25
	s_cselect_b32 s36, s16, s24
	s_cselect_b32 s27, s23, s41
	s_cselect_b32 s26, s22, s40
	s_add_i32 s31, 0, 0x14000
	v_add_u32_e32 v136, s30, v198
	v_add_u32_e32 v160, s31, v198
	ds_read_b128 v[124:127], v136
	ds_read_b128 v[128:131], v136 offset:1024
	ds_read_b128 v[132:135], v136 offset:2048
	ds_read_b128 v[136:139], v136 offset:3072
	ds_read_b128 v[148:151], v160
	ds_read_b128 v[152:155], v160 offset:1024
	ds_read_b128 v[156:159], v160 offset:2048
	ds_read_b128 v[160:163], v160 offset:3072
	v_lshl_add_u64 v[210:211], s[20:21], 0, v[184:185]
	s_add_i32 m0, s18, 0xc000
	ds_read_b128 v[164:167], v200
	ds_read_b128 v[168:171], v200 offset:1024
	ds_read_b128 v[172:175], v200 offset:2048
	ds_read_b128 v[186:189], v200 offset:3072
	ds_read_b128 v[190:193], v200 offset:4096
	ds_read_b128 v[194:197], v200 offset:5120
	ds_read_b128 v[202:205], v200 offset:6144
	ds_read_b128 v[206:209], v200 offset:7168
	global_load_lds_dwordx4 v[210:211], off
	v_lshl_add_u64 v[210:211], s[20:21], 0, v[182:183]
	s_add_i32 m0, s18, 0xe000
	s_nop 0
	global_load_lds_dwordx4 v[210:211], off
	s_waitcnt vmcnt(8)
	s_waitcnt lgkmcnt(0)
	s_barrier
	s_setprio 1
	s_waitcnt lgkmcnt(0)
	v_mfma_f32_16x16x32_bf16 v[144:147], v[124:127], v[164:167], v[144:147]
	v_mfma_f32_16x16x32_bf16 v[140:143], v[132:135], v[164:167], v[140:143]
	v_mfma_f32_16x16x32_bf16 v[112:115], v[124:127], v[172:175], v[112:115]
	v_mfma_f32_16x16x32_bf16 v[108:111], v[132:135], v[172:175], v[108:111]
	v_mfma_f32_16x16x32_bf16 v[100:103], v[124:127], v[190:193], v[100:103]
	v_mfma_f32_16x16x32_bf16 v[92:95], v[132:135], v[190:193], v[92:95]
	v_mfma_f32_16x16x32_bf16 v[84:87], v[124:127], v[202:205], v[84:87]
	v_mfma_f32_16x16x32_bf16 v[76:79], v[132:135], v[202:205], v[76:79]
	v_mfma_f32_16x16x32_bf16 v[144:147], v[128:131], v[168:171], v[144:147]
	v_mfma_f32_16x16x32_bf16 v[140:143], v[136:139], v[168:171], v[140:143]
	v_mfma_f32_16x16x32_bf16 v[112:115], v[128:131], v[186:189], v[112:115]
	v_mfma_f32_16x16x32_bf16 v[108:111], v[136:139], v[186:189], v[108:111]
	v_mfma_f32_16x16x32_bf16 v[100:103], v[128:131], v[194:197], v[100:103]
	v_mfma_f32_16x16x32_bf16 v[92:95], v[136:139], v[194:197], v[92:95]
	v_mfma_f32_16x16x32_bf16 v[84:87], v[128:131], v[206:209], v[84:87]
	v_mfma_f32_16x16x32_bf16 v[76:79], v[136:139], v[206:209], v[76:79]
	s_setprio 0
	s_setprio 1
	v_mfma_f32_16x16x32_bf16 v[120:123], v[148:151], v[164:167], v[120:123]
	v_mfma_f32_16x16x32_bf16 v[116:119], v[156:159], v[164:167], v[116:119]
	v_mfma_f32_16x16x32_bf16 v[104:107], v[148:151], v[172:175], v[104:107]
	v_mfma_f32_16x16x32_bf16 v[96:99], v[156:159], v[172:175], v[96:99]
	v_mfma_f32_16x16x32_bf16 v[88:91], v[148:151], v[190:193], v[88:91]
	v_mfma_f32_16x16x32_bf16 v[80:83], v[156:159], v[190:193], v[80:83]
	v_mfma_f32_16x16x32_bf16 v[72:75], v[148:151], v[202:205], v[72:75]
	v_mfma_f32_16x16x32_bf16 v[68:71], v[156:159], v[202:205], v[68:71]
	v_mfma_f32_16x16x32_bf16 v[120:123], v[152:155], v[168:171], v[120:123]
	v_mfma_f32_16x16x32_bf16 v[116:119], v[160:163], v[168:171], v[116:119]
	v_mfma_f32_16x16x32_bf16 v[104:107], v[152:155], v[186:189], v[104:107]
	v_mfma_f32_16x16x32_bf16 v[96:99], v[160:163], v[186:189], v[96:99]
	v_mfma_f32_16x16x32_bf16 v[88:91], v[152:155], v[194:197], v[88:91]
	v_mfma_f32_16x16x32_bf16 v[80:83], v[160:163], v[194:197], v[80:83]
	v_mfma_f32_16x16x32_bf16 v[72:75], v[152:155], v[206:209], v[72:75]
	v_mfma_f32_16x16x32_bf16 v[68:71], v[160:163], v[206:209], v[68:71]
	s_setprio 0
	s_barrier
	s_add_i32 s20, s30, s13
	v_lshl_add_u64 v[210:211], s[26:27], 0, v[2:3]
	s_mov_b32 m0, s20
	ds_read_b128 v[164:167], v200 offset:16384
	ds_read_b128 v[168:171], v200 offset:17408
	ds_read_b128 v[172:175], v200 offset:18432
	ds_read_b128 v[186:189], v200 offset:19456
	ds_read_b128 v[190:193], v200 offset:20480
	ds_read_b128 v[194:197], v200 offset:21504
	ds_read_b128 v[202:205], v200 offset:22528
	ds_read_b128 v[206:209], v200 offset:23552
	global_load_lds_dwordx4 v[210:211], off
	s_add_i32 m0, s20, 0x2000
	s_add_u32 s20, s26, 0x160000
	v_lshl_add_u64 v[212:213], s[26:27], 0, v[180:181]
	s_addc_u32 s21, s27, 0
	s_add_i32 s30, s31, s13
	global_load_lds_dwordx4 v[212:213], off
	v_lshl_add_u64 v[214:215], s[20:21], 0, v[2:3]
	s_mov_b32 m0, s30
	v_lshl_add_u64 v[216:217], s[36:37], 0, v[178:179]
	global_load_lds_dwordx4 v[214:215], off
	v_lshl_add_u64 v[214:215], s[20:21], 0, v[180:181]
	s_add_i32 m0, s30, 0x2000
	s_nop 0
	global_load_lds_dwordx4 v[214:215], off
	v_lshl_add_u64 v[214:215], s[36:37], 0, v[176:177]
	s_mov_b32 m0, s18
	s_nop 0
	global_load_lds_dwordx4 v[214:215], off
	s_mov_b32 m0, s44
	s_nop 0
	global_load_lds_dwordx4 v[216:217], off
	s_waitcnt vmcnt(8)
	s_waitcnt lgkmcnt(0)
	s_barrier
; #define PG8_STAGE(bufoff, gbase, voff) do { _Pragma("unroll") for (int _i = 0; _i < 2; ++_i) \
;         __builtin_amdgcn_global_load_lds((const unsigned*)((const char*)(gbase) + (voff)[_i]), (PG8_LAS unsigned*)(lds + (bufoff) + ldsw + _i * 8192), 16, 0, 0); } while (0)
; #define PG8_LDA(dst, b, h) do { _Pragma("unroll") for (int m = 0; m < 4; ++m) _Pragma("unroll") for (int k = 0; k < 2; ++k) dst[m][k] = *(const PG8_LAS bf16x8*)(lds + PG8_SA(b, h) + aoff + m * 2048 + k * 1024); } while (0)
; #define PG8_LDB(dst, b, h) do { _Pragma("unroll") for (int n = 0; n < 2; ++n) _Pragma("unroll") for (int k = 0; k < 2; ++k) dst[n][k] = *(const PG8_LAS bf16x8*)(lds + PG8_SB(b, h) + boff + n * 2048 + k * 1024); } while (0)
; #define PG8_MMA(ai, bj, At, Bt) do { __builtin_amdgcn_s_setprio(1); _Pragma("unroll") for (int m = 0; m < 4; ++m) _Pragma("unroll") for (int n = 0; n < 2; ++n) _Pragma("unroll") for (int k = 0; k < 2; ++k) \
;         acc[ai][bj][m][n] = __builtin_amdgcn_mfma_f32_16x16x32_bf16(Bt[n][k], At[m][k], acc[ai][bj][m][n], 0, 0, 0); __builtin_amdgcn_s_setprio(0); } while (0)
; #define PG8_WAIT_V(n) asm volatile("s_waitcnt vmcnt(" #n ")" ::: "memory")
; #define PG8_WAIT_L(n) asm volatile("s_waitcnt lgkmcnt(" #n ")" ::: "memory")
; #define PG8_BAR __builtin_amdgcn_s_barrier()
; #define PG8_SCHED __builtin_amdgcn_sched_barrier(0)
; template <class Epi, class Sched, bool ALIGN_EPI = false, bool SP2 = false>
; __device__ __forceinline__ void gemm_phase(PG8_LAS unsigned char* lds, const Gemm g, const Sched& S, const Epi& E) {
;     ...
;             PG8_WAIT_V(8); PG8_WAIT_L(0); PG8_BAR; PG8_MMA(1, 0, At, B0); PG8_MMA(1, 1, At, B1); PG8_BAR; PG8_SCHED;
;             PG8_LDB(B0, 1, 0); PG8_LDB(B1, 1, 1); PG8_SCHED; PG8_LDA(At, 1, 0); PG8_STAGE(PG8_SA(0, 1), a2 + hstep, voffA);
;             PG8_WAIT_V(8); PG8_WAIT_L(0); PG8_BAR; PG8_MMA(0, 0, At, B0); PG8_MMA(0, 1, At, B1); PG8_BAR; PG8_SCHED;
	s_setprio 1
	s_waitcnt lgkmcnt(0)
	v_mfma_f32_16x16x32_bf16 v[64:67], v[124:127], v[164:167], v[64:67]
	v_mfma_f32_16x16x32_bf16 v[60:63], v[132:135], v[164:167], v[60:63]
	v_mfma_f32_16x16x32_bf16 v[52:55], v[124:127], v[172:175], v[52:55]
	v_mfma_f32_16x16x32_bf16 v[44:47], v[132:135], v[172:175], v[44:47]
	v_mfma_f32_16x16x32_bf16 v[36:39], v[124:127], v[190:193], v[36:39]
	v_mfma_f32_16x16x32_bf16 v[28:31], v[132:135], v[190:193], v[28:31]
	v_mfma_f32_16x16x32_bf16 v[20:23], v[124:127], v[202:205], v[20:23]
	v_mfma_f32_16x16x32_bf16 v[12:15], v[132:135], v[202:205], v[12:15]
	v_mfma_f32_16x16x32_bf16 v[64:67], v[128:131], v[168:171], v[64:67]
	v_mfma_f32_16x16x32_bf16 v[60:63], v[136:139], v[168:171], v[60:63]
	v_mfma_f32_16x16x32_bf16 v[52:55], v[128:131], v[186:189], v[52:55]
	v_mfma_f32_16x16x32_bf16 v[44:47], v[136:139], v[186:189], v[44:47]
	v_mfma_f32_16x16x32_bf16 v[36:39], v[128:131], v[194:197], v[36:39]
	v_mfma_f32_16x16x32_bf16 v[28:31], v[136:139], v[194:197], v[28:31]
	v_mfma_f32_16x16x32_bf16 v[20:23], v[128:131], v[206:209], v[20:23]
	v_mfma_f32_16x16x32_bf16 v[12:15], v[136:139], v[206:209], v[12:15]
	s_setprio 0
	s_setprio 1
	v_mfma_f32_16x16x32_bf16 v[56:59], v[148:151], v[164:167], v[56:59]
	v_mfma_f32_16x16x32_bf16 v[48:51], v[156:159], v[164:167], v[48:51]
	v_mfma_f32_16x16x32_bf16 v[40:43], v[148:151], v[172:175], v[40:43]
	v_mfma_f32_16x16x32_bf16 v[32:35], v[156:159], v[172:175], v[32:35]
	v_mfma_f32_16x16x32_bf16 v[24:27], v[148:151], v[190:193], v[24:27]
	v_mfma_f32_16x16x32_bf16 v[16:19], v[156:159], v[190:193], v[16:19]
	v_mfma_f32_16x16x32_bf16 v[8:11], v[148:151], v[202:205], v[8:11]
	v_mfma_f32_16x16x32_bf16 v[4:7], v[156:159], v[202:205], v[4:7]
	v_mfma_f32_16x16x32_bf16 v[56:59], v[152:155], v[168:171], v[56:59]
	v_mfma_f32_16x16x32_bf16 v[48:51], v[160:163], v[168:171], v[48:51]
	v_mfma_f32_16x16x32_bf16 v[40:43], v[152:155], v[186:189], v[40:43]
	v_mfma_f32_16x16x32_bf16 v[32:35], v[160:163], v[186:189], v[32:35]
	v_mfma_f32_16x16x32_bf16 v[24:27], v[152:155], v[194:197], v[24:27]
	v_mfma_f32_16x16x32_bf16 v[16:19], v[160:163], v[194:197], v[16:19]
	v_mfma_f32_16x16x32_bf16 v[8:11], v[152:155], v[206:209], v[8:11]
	v_mfma_f32_16x16x32_bf16 v[4:7], v[160:163], v[206:209], v[4:7]
	s_setprio 0
	s_barrier
	s_add_i32 s30, 0, 0x18000
	s_add_i32 s31, 0, 0x1c000
	v_add_u32_e32 v136, s30, v198
	v_add_u32_e32 v160, s31, v198
	ds_read_b128 v[124:127], v136
	ds_read_b128 v[128:131], v136 offset:1024
	ds_read_b128 v[132:135], v136 offset:2048
	ds_read_b128 v[136:139], v136 offset:3072
	ds_read_b128 v[148:151], v160
	ds_read_b128 v[152:155], v160 offset:1024
	ds_read_b128 v[156:159], v160 offset:2048
	ds_read_b128 v[160:163], v160 offset:3072
	s_add_u32 s20, s36, 0x160000
	s_addc_u32 s21, s37, 0
	s_mov_b32 m0, s45
	v_lshl_add_u64 v[218:219], s[20:21], 0, v[176:177]
	ds_read_b128 v[164:167], v200 offset:32768
	ds_read_b128 v[168:171], v200 offset:33792
	ds_read_b128 v[172:175], v200 offset:34816
	ds_read_b128 v[186:189], v200 offset:35840
	ds_read_b128 v[190:193], v200 offset:36864
	ds_read_b128 v[194:197], v200 offset:37888
	ds_read_b128 v[202:205], v200 offset:38912
	ds_read_b128 v[206:209], v200 offset:39936
	global_load_lds_dwordx4 v[218:219], off
	v_lshl_add_u64 v[218:219], s[20:21], 0, v[178:179]
	s_mov_b32 m0, s46
	s_nop 0
	global_load_lds_dwordx4 v[218:219], off
	s_waitcnt vmcnt(8)
	s_waitcnt lgkmcnt(0)
	s_barrier
	s_setprio 1
	s_waitcnt lgkmcnt(0)
	v_mfma_f32_16x16x32_bf16 v[144:147], v[124:127], v[164:167], v[144:147]
	v_mfma_f32_16x16x32_bf16 v[140:143], v[132:135], v[164:167], v[140:143]
	v_mfma_f32_16x16x32_bf16 v[112:115], v[124:127], v[172:175], v[112:115]
	v_mfma_f32_16x16x32_bf16 v[108:111], v[132:135], v[172:175], v[108:111]
	v_mfma_f32_16x16x32_bf16 v[100:103], v[124:127], v[190:193], v[100:103]
	v_mfma_f32_16x16x32_bf16 v[92:95], v[132:135], v[190:193], v[92:95]
	v_mfma_f32_16x16x32_bf16 v[84:87], v[124:127], v[202:205], v[84:87]
	v_mfma_f32_16x16x32_bf16 v[76:79], v[132:135], v[202:205], v[76:79]
	v_mfma_f32_16x16x32_bf16 v[144:147], v[128:131], v[168:171], v[144:147]
	v_mfma_f32_16x16x32_bf16 v[140:143], v[136:139], v[168:171], v[140:143]
	v_mfma_f32_16x16x32_bf16 v[112:115], v[128:131], v[186:189], v[112:115]
	v_mfma_f32_16x16x32_bf16 v[108:111], v[136:139], v[186:189], v[108:111]
	v_mfma_f32_16x16x32_bf16 v[100:103], v[128:131], v[194:197], v[100:103]
	v_mfma_f32_16x16x32_bf16 v[92:95], v[136:139], v[194:197], v[92:95]
	v_mfma_f32_16x16x32_bf16 v[84:87], v[128:131], v[206:209], v[84:87]
	v_mfma_f32_16x16x32_bf16 v[76:79], v[136:139], v[206:209], v[76:79]
	s_setprio 0
	s_setprio 1
	v_mfma_f32_16x16x32_bf16 v[120:123], v[148:151], v[164:167], v[120:123]
	v_mfma_f32_16x16x32_bf16 v[116:119], v[156:159], v[164:167], v[116:119]
	v_mfma_f32_16x16x32_bf16 v[104:107], v[148:151], v[172:175], v[104:107]
	v_mfma_f32_16x16x32_bf16 v[96:99], v[156:159], v[172:175], v[96:99]
	v_mfma_f32_16x16x32_bf16 v[88:91], v[148:151], v[190:193], v[88:91]
	v_mfma_f32_16x16x32_bf16 v[80:83], v[156:159], v[190:193], v[80:83]
	v_mfma_f32_16x16x32_bf16 v[72:75], v[148:151], v[202:205], v[72:75]
	v_mfma_f32_16x16x32_bf16 v[68:71], v[156:159], v[202:205], v[68:71]
	v_mfma_f32_16x16x32_bf16 v[120:123], v[152:155], v[168:171], v[120:123]
	v_mfma_f32_16x16x32_bf16 v[116:119], v[160:163], v[168:171], v[116:119]
	v_mfma_f32_16x16x32_bf16 v[104:107], v[152:155], v[186:189], v[104:107]
	v_mfma_f32_16x16x32_bf16 v[96:99], v[160:163], v[186:189], v[96:99]
	v_mfma_f32_16x16x32_bf16 v[88:91], v[152:155], v[194:197], v[88:91]
	v_mfma_f32_16x16x32_bf16 v[80:83], v[160:163], v[194:197], v[80:83]
	v_mfma_f32_16x16x32_bf16 v[72:75], v[152:155], v[206:209], v[72:75]
	v_mfma_f32_16x16x32_bf16 v[68:71], v[160:163], v[206:209], v[68:71]
	s_setprio 0
	s_barrier
;     __device__ __forceinline__ void operator()(const f32x4 (&acc)[2][2][4][2], const Unit& u, int wr, int wc, int fr, int fq) const {
;         const int row0 = u.pm * BM + wr * 64 + fr; const int col0 = u.pn * BM + wc * 32 + 8 * fq;
;         const float* gp = gate + (size_t)((u.pm * BM) >> 12) * gstride + col0;
;         f32x4 gv[2][2];
; #pragma unroll
;         for (int bj = 0; bj < 2; ++bj)
; #pragma unroll
;             for (int n = 0; n < 2; ++n) gv[bj][n] = *(const f32x4*)(gp + bj * HALF + n * 4);
;         if (base_f32) { const float* bp = (const float*)base;
; #pragma unroll
;             for (int ai = 0; ai < 2; ++ai)
; #pragma unroll
;                 for (int m2 = 0; m2 < 2; ++m2) { f32x4 bs[2][2][2];
; #pragma unroll
;                     for (int mm = 0; mm < 2; ++mm) { const size_t off = (size_t)(row0 + ai * HALF + (2 * m2 + mm) * 16) * ldc + col0;
; #pragma unroll
;                         for (int bj = 0; bj < 2; ++bj)
; #pragma unroll
;                             for (int n = 0; n < 2; ++n) bs[mm][bj][n] = *(const f32x4*)(bp + off + bj * HALF + n * 4); }
; #pragma unroll
;                     for (int mm = 0; mm < 2; ++mm) { const size_t off = (size_t)(row0 + ai * HALF + (2 * m2 + mm) * 16) * ldc + col0;
; #pragma unroll
;                         for (int bj = 0; bj < 2; ++bj) { const f32x4 v0 = bs[mm][bj][0] + gv[bj][0] * acc[ai][bj][2 * m2 + mm][0], v1 = bs[mm][bj][1] + gv[bj][1] * acc[ai][bj][2 * m2 + mm][1];
;                             u32x4 w; w.x = cvt_pk_bf16(v0[0], v0[1]); w.y = cvt_pk_bf16(v0[2], v0[3]); w.z = cvt_pk_bf16(v1[0], v1[1]); w.w = cvt_pk_bf16(v1[2], v1[3]);
;                             *(u32x4*)(out + off + bj * HALF) = w; } }
;                     asm volatile("" ::: "memory"); }
;         } else { const bf16_t* bp = (const bf16_t*)base;
; #pragma unroll
;             for (int ai = 0; ai < 2; ++ai) { u32x4 bs[4][2];
; #pragma unroll
; template <class Epi, class Sched, bool ALIGN_EPI = false, bool SP2 = false>
; __device__ __forceinline__ void gemm_phase(PG8_LAS unsigned char* lds, const Gemm g, const Sched& S, const Epi& E) {
;     ...
;             PG8_LDA(At, 1, 1); PG8_STAGE(PG8_SB(1, 0), b3, voffB); PG8_STAGE(PG8_SB(1, 1), b3 + hstep, voffB); PG8_STAGE(PG8_SA(1, 0), a3, voffA);
;             PG8_WAIT_V(8); PG8_WAIT_L(0); PG8_BAR; PG8_MMA(1, 0, At, B0); PG8_MMA(1, 1, At, B1); PG8_BAR; PG8_SCHED;
	s_add_i32 s20, s30, s13
	v_lshl_add_u64 v[210:211], v[210:211], 0, s[28:29]
	s_mov_b32 m0, s20
	ds_read_b128 v[164:167], v200 offset:49152
	ds_read_b128 v[168:171], v200 offset:50176
	ds_read_b128 v[172:175], v200 offset:51200
	ds_read_b128 v[186:189], v200 offset:52224
	ds_read_b128 v[190:193], v200 offset:53248
	ds_read_b128 v[194:197], v200 offset:54272
	ds_read_b128 v[202:205], v200 offset:55296
	ds_read_b128 v[206:209], v200 offset:56320
	global_load_lds_dwordx4 v[210:211], off
	s_add_i32 m0, s20, 0x2000
	s_add_u32 s20, s26, 0x160080
	v_lshl_add_u64 v[210:211], v[212:213], 0, s[28:29]
	s_addc_u32 s21, s27, 0
	s_add_i32 s26, s31, s13
	global_load_lds_dwordx4 v[210:211], off
	v_lshl_add_u64 v[210:211], s[20:21], 0, v[2:3]
	s_mov_b32 m0, s26
	s_nop 0
	global_load_lds_dwordx4 v[210:211], off
	v_lshl_add_u64 v[210:211], s[20:21], 0, v[180:181]
	s_add_i32 m0, s26, 0x2000
	s_nop 0
	global_load_lds_dwordx4 v[210:211], off
	v_lshl_add_u64 v[210:211], v[214:215], 0, s[28:29]
	s_mov_b32 m0, s49
	s_nop 0
	global_load_lds_dwordx4 v[210:211], off
	v_lshl_add_u64 v[210:211], v[216:217], 0, s[28:29]
	s_mov_b32 m0, s50
	s_nop 0
	global_load_lds_dwordx4 v[210:211], off
	s_waitcnt vmcnt(8)
	s_waitcnt lgkmcnt(0)
	s_barrier
	s_setprio 1
	s_waitcnt lgkmcnt(0)
	v_mfma_f32_16x16x32_bf16 v[64:67], v[124:127], v[164:167], v[64:67]
	v_mfma_f32_16x16x32_bf16 v[60:63], v[132:135], v[164:167], v[60:63]
	v_mfma_f32_16x16x32_bf16 v[52:55], v[124:127], v[172:175], v[52:55]
	v_mfma_f32_16x16x32_bf16 v[44:47], v[132:135], v[172:175], v[44:47]
	v_mfma_f32_16x16x32_bf16 v[36:39], v[124:127], v[190:193], v[36:39]
	v_mfma_f32_16x16x32_bf16 v[28:31], v[132:135], v[190:193], v[28:31]
	v_mfma_f32_16x16x32_bf16 v[20:23], v[124:127], v[202:205], v[20:23]
	v_mfma_f32_16x16x32_bf16 v[12:15], v[132:135], v[202:205], v[12:15]
	v_mfma_f32_16x16x32_bf16 v[64:67], v[128:131], v[168:171], v[64:67]
	v_mfma_f32_16x16x32_bf16 v[60:63], v[136:139], v[168:171], v[60:63]
	v_mfma_f32_16x16x32_bf16 v[52:55], v[128:131], v[186:189], v[52:55]
	v_mfma_f32_16x16x32_bf16 v[44:47], v[136:139], v[186:189], v[44:47]
	v_mfma_f32_16x16x32_bf16 v[36:39], v[128:131], v[194:197], v[36:39]
	v_mfma_f32_16x16x32_bf16 v[28:31], v[136:139], v[194:197], v[28:31]
	v_mfma_f32_16x16x32_bf16 v[20:23], v[128:131], v[206:209], v[20:23]
	v_mfma_f32_16x16x32_bf16 v[12:15], v[136:139], v[206:209], v[12:15]
	s_setprio 0
	s_setprio 1
	v_mfma_f32_16x16x32_bf16 v[56:59], v[148:151], v[164:167], v[56:59]
	v_mfma_f32_16x16x32_bf16 v[48:51], v[156:159], v[164:167], v[48:51]
	v_mfma_f32_16x16x32_bf16 v[40:43], v[148:151], v[172:175], v[40:43]
	v_mfma_f32_16x16x32_bf16 v[32:35], v[156:159], v[172:175], v[32:35]
	v_mfma_f32_16x16x32_bf16 v[24:27], v[148:151], v[190:193], v[24:27]
	v_mfma_f32_16x16x32_bf16 v[16:19], v[156:159], v[190:193], v[16:19]
	v_mfma_f32_16x16x32_bf16 v[8:11], v[148:151], v[202:205], v[8:11]
	v_mfma_f32_16x16x32_bf16 v[4:7], v[156:159], v[202:205], v[4:7]
	v_mfma_f32_16x16x32_bf16 v[56:59], v[152:155], v[168:171], v[56:59]
	v_mfma_f32_16x16x32_bf16 v[48:51], v[160:163], v[168:171], v[48:51]
	v_mfma_f32_16x16x32_bf16 v[40:43], v[152:155], v[186:189], v[40:43]
	v_mfma_f32_16x16x32_bf16 v[32:35], v[160:163], v[186:189], v[32:35]
	v_mfma_f32_16x16x32_bf16 v[24:27], v[152:155], v[194:197], v[24:27]
	v_mfma_f32_16x16x32_bf16 v[16:19], v[160:163], v[194:197], v[16:19]
	v_mfma_f32_16x16x32_bf16 v[8:11], v[152:155], v[206:209], v[8:11]
	v_mfma_f32_16x16x32_bf16 v[4:7], v[160:163], v[206:209], v[4:7]
	s_setprio 0
	s_barrier
	s_add_i32 s42, s42, 2
	s_add_u32 s40, s40, 0x100
	s_addc_u32 s41, s41, 0
	s_cmpk_gt_u32 s42, 0x55
	s_mov_b64 s[20:21], s[24:25]
	s_cbranch_scc0 .LBB0_2238
	v_lshl_or_b32 v148, s54, 8, v199
	s_ashr_i32 s20, s33, 4
	s_mul_hi_i32 s21, s20, 0xc000
	s_mul_i32 s20, s20, 0xc000
	v_ashrrev_i32_e32 v149, 31, v148
	v_lshl_add_u32 v150, s33, 8, v1
	s_add_u32 s20, s47, s20
	v_ashrrev_i32_e32 v151, 31, v150
	v_lshlrev_b64 v[186:187], 1, v[148:149]
	s_addc_u32 s21, s48, s21
	v_lshl_add_u64 v[188:189], s[14:15], 0, v[186:187]
	v_lshlrev_b64 v[190:191], 12, v[150:151]
	v_lshl_add_u64 v[124:125], v[148:149], 2, s[20:21]
	v_lshl_add_u64 v[148:149], v[188:189], 0, v[190:191]
	flat_load_dwordx4 v[136:139], v[124:125]
	flat_load_dwordx4 v[132:135], v[124:125] offset:16
	flat_load_dwordx4 v[128:131], v[124:125] offset:512
	s_nop 0
	flat_load_dwordx4 v[124:127], v[124:125] offset:528
	s_nop 0
	flat_load_dwordx4 v[202:205], v[148:149]
	flat_load_dwordx4 v[172:175], v[148:149] offset:256
	v_or_b32_e32 v148, 16, v150
	v_ashrrev_i32_e32 v149, 31, v148
	v_lshlrev_b64 v[196:197], 12, v[148:149]
	v_lshl_add_u64 v[148:149], v[188:189], 0, v[196:197]
	flat_load_dwordx4 v[168:171], v[148:149]
	flat_load_dwordx4 v[164:167], v[148:149] offset:256
	v_or_b32_e32 v148, 32, v150
	v_ashrrev_i32_e32 v149, 31, v148
	v_lshlrev_b64 v[194:195], 12, v[148:149]
	v_lshl_add_u64 v[148:149], v[188:189], 0, v[194:195]
	flat_load_dwordx4 v[160:163], v[148:149]
	flat_load_dwordx4 v[152:155], v[148:149] offset:256
	v_or_b32_e32 v148, 48, v150
	v_ashrrev_i32_e32 v149, 31, v148
	v_lshlrev_b64 v[192:193], 12, v[148:149]
	v_lshl_add_u64 v[148:149], v[188:189], 0, v[192:193]
	flat_load_dwordx4 v[156:159], v[148:149]
	s_nop 0
	flat_load_dwordx4 v[148:151], v[148:149] offset:256
	v_lshl_add_u64 v[244:245], v[188:189], 0, v[190:191]
	s_mov_b64 s[20:21], 0x80000
	v_lshl_add_u64 v[246:247], v[244:245], 0, s[20:21]
	global_load_dwordx4 v[248:251], v[246:247], off
	global_load_dwordx4 v[248:251], v[246:247], off offset:256
	s_mov_b64 s[20:21], 0x90000
	v_lshl_add_u64 v[246:247], v[244:245], 0, s[20:21]
	global_load_dwordx4 v[248:251], v[246:247], off
	global_load_dwordx4 v[248:251], v[246:247], off offset:256
	s_mov_b64 s[20:21], 0xa0000
	v_lshl_add_u64 v[246:247], v[244:245], 0, s[20:21]
	global_load_dwordx4 v[248:251], v[246:247], off
	global_load_dwordx4 v[248:251], v[246:247], off offset:256
	s_mov_b64 s[20:21], 0xb0000
	v_lshl_add_u64 v[246:247], v[244:245], 0, s[20:21]
	global_load_dwordx4 v[248:251], v[246:247], off
	global_load_dwordx4 v[248:251], v[246:247], off offset:256
	s_mov_b64 s[20:21], 0x80000
	s_and_b64 vcc, exec, s[38:39]
	s_mov_b32 s54, s52
	s_mov_b32 s33, s53
	s_mov_b64 s[24:25], s[22:23]
	s_waitcnt vmcnt(0) lgkmcnt(0)
; __device__ __forceinline__ unsigned cvt_pk_bf16(float lo, float hi) { unsigned r; asm volatile("v_cvt_pk_bf16_f32 %0, %1, %2" : "=v"(r) : "v"(lo), "v"(hi)); return r; }
;     __device__ __forceinline__ void operator()(const f32x4 (&acc)[2][2][4][2], const Unit& u, int wr, int wc, int fr, int fq) const {
;     ...
;                 for (int m = 0; m < 4; ++m) { const size_t off = (size_t)(row0 + ai * HALF + m * 16) * ldc + col0;
; #pragma unroll
;                     for (int bj = 0; bj < 2; ++bj) { const u32x4 r = bs[m][bj]; const f32x4 a0 = acc[ai][bj][m][0], a1 = acc[ai][bj][m][1];
;                         u32x4 w;
;                         w.x = cvt_pk_bf16(__builtin_bit_cast(float, r.x << 16) + gv[bj][0][0] * a0[0], __builtin_bit_cast(float, r.x & 0xffff0000u) + gv[bj][0][1] * a0[1]);
;                         w.y = cvt_pk_bf16(__builtin_bit_cast(float, r.y << 16) + gv[bj][0][2] * a0[2], __builtin_bit_cast(float, r.y & 0xffff0000u) + gv[bj][0][3] * a0[3]);
;                         w.z = cvt_pk_bf16(__builtin_bit_cast(float, r.z << 16) + gv[bj][1][0] * a1[0], __builtin_bit_cast(float, r.z & 0xffff0000u) + gv[bj][1][1] * a1[1]);
;                         w.w = cvt_pk_bf16(__builtin_bit_cast(float, r.w << 16) + gv[bj][1][2] * a1[2], __builtin_bit_cast(float, r.w & 0xffff0000u) + gv[bj][1][3] * a1[3]);
;                         *(u32x4*)(out + off + bj * HALF) = w; } }
	v_lshlrev_b32_e32 v201, 16, v202
	v_fmac_f32_e32 v201, v144, v136
	v_and_b32_e32 v144, 0xffff0000, v202
	v_fmac_f32_e32 v144, v145, v137
	v_lshlrev_b32_e32 v145, 16, v203
	v_fmac_f32_e32 v145, v146, v138
	v_and_b32_e32 v146, 0xffff0000, v203
	v_fmac_f32_e32 v146, v147, v139
	v_cvt_pk_bf16_f32 v144, v201, v144
	v_cvt_pk_bf16_f32 v145, v145, v146
	v_lshlrev_b32_e32 v146, 16, v204
	v_fmac_f32_e32 v146, v140, v132
	v_and_b32_e32 v140, 0xffff0000, v204
	v_fmac_f32_e32 v140, v141, v133
	v_cvt_pk_bf16_f32 v146, v146, v140
	v_lshlrev_b32_e32 v140, 16, v205
	v_fmac_f32_e32 v140, v142, v134
	v_lshlrev_b32_e32 v142, 16, v172
	v_and_b32_e32 v141, 0xffff0000, v205
	v_fmac_f32_e32 v142, v120, v128
	v_and_b32_e32 v120, 0xffff0000, v172
	v_fmac_f32_e32 v141, v143, v135
	v_fmac_f32_e32 v120, v121, v129
	v_lshlrev_b32_e32 v121, 16, v173
	v_cvt_pk_bf16_f32 v147, v140, v141
	v_lshl_add_u64 v[140:141], s[14:15], 0, v[190:191]
	v_fmac_f32_e32 v121, v122, v130
	v_and_b32_e32 v122, 0xffff0000, v173
	v_lshl_add_u64 v[140:141], v[140:141], 0, v[186:187]
	v_fmac_f32_e32 v122, v123, v131
	flat_store_dwordx4 v[140:141], v[144:147]
	v_cvt_pk_bf16_f32 v120, v142, v120
	v_cvt_pk_bf16_f32 v121, v121, v122
	v_lshlrev_b32_e32 v122, 16, v174
	v_fmac_f32_e32 v122, v116, v124
	v_and_b32_e32 v116, 0xffff0000, v174
	v_fmac_f32_e32 v116, v117, v125
	v_cvt_pk_bf16_f32 v122, v122, v116
	v_lshlrev_b32_e32 v116, 16, v175
	v_fmac_f32_e32 v116, v118, v126
	v_and_b32_e32 v117, 0xffff0000, v175
	v_fmac_f32_e32 v117, v119, v127
	v_cvt_pk_bf16_f32 v123, v116, v117
	v_lshlrev_b32_e32 v116, 16, v168
	v_fmac_f32_e32 v116, v112, v136
	v_and_b32_e32 v112, 0xffff0000, v168
	v_fmac_f32_e32 v112, v113, v137
	v_lshlrev_b32_e32 v113, 16, v169
	v_fmac_f32_e32 v113, v114, v138
	v_and_b32_e32 v114, 0xffff0000, v169
	v_fmac_f32_e32 v114, v115, v139
	flat_store_dwordx4 v[140:141], v[120:123] offset:256
	v_cvt_pk_bf16_f32 v112, v116, v112
	v_cvt_pk_bf16_f32 v113, v113, v114
	v_lshlrev_b32_e32 v114, 16, v170
	v_fmac_f32_e32 v114, v108, v132
	v_and_b32_e32 v108, 0xffff0000, v170
	v_fmac_f32_e32 v108, v109, v133
	v_cvt_pk_bf16_f32 v114, v114, v108
	v_lshlrev_b32_e32 v108, 16, v171
	v_fmac_f32_e32 v108, v110, v134
	v_lshlrev_b32_e32 v110, 16, v164
	v_and_b32_e32 v109, 0xffff0000, v171
	v_fmac_f32_e32 v110, v104, v128
	v_and_b32_e32 v104, 0xffff0000, v164
	v_fmac_f32_e32 v109, v111, v135
	v_fmac_f32_e32 v104, v105, v129
	v_lshlrev_b32_e32 v105, 16, v165
	v_cvt_pk_bf16_f32 v115, v108, v109
	v_lshl_add_u64 v[108:109], s[14:15], 0, v[196:197]
	v_fmac_f32_e32 v105, v106, v130
	v_and_b32_e32 v106, 0xffff0000, v165
	v_lshl_add_u64 v[108:109], v[108:109], 0, v[186:187]
	v_fmac_f32_e32 v106, v107, v131
	flat_store_dwordx4 v[108:109], v[112:115]
	v_cvt_pk_bf16_f32 v104, v110, v104
	v_cvt_pk_bf16_f32 v105, v105, v106
	v_lshlrev_b32_e32 v106, 16, v166
	v_fmac_f32_e32 v106, v96, v124
	v_and_b32_e32 v96, 0xffff0000, v166
	v_fmac_f32_e32 v96, v97, v125
	v_cvt_pk_bf16_f32 v106, v106, v96
	v_lshlrev_b32_e32 v96, 16, v167
	v_and_b32_e32 v97, 0xffff0000, v167
	v_fmac_f32_e32 v96, v98, v126
	v_fmac_f32_e32 v97, v99, v127
	v_cvt_pk_bf16_f32 v107, v96, v97
	v_lshlrev_b32_e32 v96, 16, v160
	v_and_b32_e32 v97, 0xffff0000, v160
	v_fmac_f32_e32 v96, v100, v136
	v_fmac_f32_e32 v97, v101, v137
	flat_store_dwordx4 v[108:109], v[104:107] offset:256
	v_cvt_pk_bf16_f32 v96, v96, v97
	v_lshlrev_b32_e32 v97, 16, v161
	v_and_b32_e32 v98, 0xffff0000, v161
	v_fmac_f32_e32 v97, v102, v138
	v_fmac_f32_e32 v98, v103, v139
	v_cvt_pk_bf16_f32 v97, v97, v98
	v_lshlrev_b32_e32 v98, 16, v162
	v_fmac_f32_e32 v98, v92, v132
	v_and_b32_e32 v92, 0xffff0000, v162
	v_fmac_f32_e32 v92, v93, v133
	v_cvt_pk_bf16_f32 v98, v98, v92
	v_lshlrev_b32_e32 v92, 16, v163
	v_fmac_f32_e32 v92, v94, v134
	v_lshlrev_b32_e32 v94, 16, v152
	v_and_b32_e32 v93, 0xffff0000, v163
	v_fmac_f32_e32 v94, v88, v128
	v_and_b32_e32 v88, 0xffff0000, v152
	v_fmac_f32_e32 v93, v95, v135
	v_fmac_f32_e32 v88, v89, v129
	v_lshlrev_b32_e32 v89, 16, v153
	v_cvt_pk_bf16_f32 v99, v92, v93
	v_lshl_add_u64 v[92:93], s[14:15], 0, v[194:195]
	v_fmac_f32_e32 v89, v90, v130
	v_and_b32_e32 v90, 0xffff0000, v153
	v_lshl_add_u64 v[92:93], v[92:93], 0, v[186:187]
	v_fmac_f32_e32 v90, v91, v131
	flat_store_dwordx4 v[92:93], v[96:99]
	v_cvt_pk_bf16_f32 v88, v94, v88
	v_cvt_pk_bf16_f32 v89, v89, v90
	v_lshlrev_b32_e32 v90, 16, v154
	v_fmac_f32_e32 v90, v80, v124
	v_and_b32_e32 v80, 0xffff0000, v154
	v_fmac_f32_e32 v80, v81, v125
	v_cvt_pk_bf16_f32 v90, v90, v80
	v_lshlrev_b32_e32 v80, 16, v155
	v_and_b32_e32 v81, 0xffff0000, v155
	v_fmac_f32_e32 v80, v82, v126
	v_fmac_f32_e32 v81, v83, v127
	v_cvt_pk_bf16_f32 v91, v80, v81
	v_lshlrev_b32_e32 v80, 16, v156
	v_and_b32_e32 v81, 0xffff0000, v156
	v_fmac_f32_e32 v80, v84, v136
	v_fmac_f32_e32 v81, v85, v137
	flat_store_dwordx4 v[92:93], v[88:91] offset:256
	v_cvt_pk_bf16_f32 v80, v80, v81
	v_lshlrev_b32_e32 v81, 16, v157
	v_and_b32_e32 v82, 0xffff0000, v157
	v_fmac_f32_e32 v81, v86, v138
	v_fmac_f32_e32 v82, v87, v139
	v_cvt_pk_bf16_f32 v81, v81, v82
	v_lshlrev_b32_e32 v82, 16, v158
	v_fmac_f32_e32 v82, v76, v132
	v_and_b32_e32 v76, 0xffff0000, v158
	v_fmac_f32_e32 v76, v77, v133
	v_cvt_pk_bf16_f32 v82, v82, v76
	v_lshlrev_b32_e32 v76, 16, v159
	v_fmac_f32_e32 v76, v78, v134
	v_lshlrev_b32_e32 v78, 16, v148
	v_and_b32_e32 v77, 0xffff0000, v159
	v_fmac_f32_e32 v78, v72, v128
	v_and_b32_e32 v72, 0xffff0000, v148
	v_fmac_f32_e32 v77, v79, v135
	v_fmac_f32_e32 v72, v73, v129
	v_lshlrev_b32_e32 v73, 16, v149
	v_cvt_pk_bf16_f32 v83, v76, v77
	v_lshl_add_u64 v[76:77], s[14:15], 0, v[192:193]
	v_fmac_f32_e32 v73, v74, v130
	v_and_b32_e32 v74, 0xffff0000, v149
; __device__ __forceinline__ unsigned cvt_pk_bf16(float lo, float hi) { unsigned r; asm volatile("v_cvt_pk_bf16_f32 %0, %1, %2" : "=v"(r) : "v"(lo), "v"(hi)); return r; }
;     __device__ __forceinline__ void operator()(const f32x4 (&acc)[2][2][4][2], const Unit& u, int wr, int wc, int fr, int fq) const {
;     ...
;             for (int ai = 0; ai < 2; ++ai) { u32x4 bs[4][2];
; #pragma unroll
;                 for (int m = 0; m < 4; ++m) { const size_t off = (size_t)(row0 + ai * HALF + m * 16) * ldc + col0;
; #pragma unroll
;                     for (int bj = 0; bj < 2; ++bj) bs[m][bj] = *(const u32x4*)(bp + off + bj * HALF); }
; #pragma unroll
;                 for (int m = 0; m < 4; ++m) { const size_t off = (size_t)(row0 + ai * HALF + m * 16) * ldc + col0;
; #pragma unroll
;                     for (int bj = 0; bj < 2; ++bj) { const u32x4 r = bs[m][bj]; const f32x4 a0 = acc[ai][bj][m][0], a1 = acc[ai][bj][m][1];
;                         u32x4 w;
;                         w.x = cvt_pk_bf16(__builtin_bit_cast(float, r.x << 16) + gv[bj][0][0] * a0[0], __builtin_bit_cast(float, r.x & 0xffff0000u) + gv[bj][0][1] * a0[1]);
;                         w.y = cvt_pk_bf16(__builtin_bit_cast(float, r.y << 16) + gv[bj][0][2] * a0[2], __builtin_bit_cast(float, r.y & 0xffff0000u) + gv[bj][0][3] * a0[3]);
;                         w.z = cvt_pk_bf16(__builtin_bit_cast(float, r.z << 16) + gv[bj][1][0] * a1[0], __builtin_bit_cast(float, r.z & 0xffff0000u) + gv[bj][1][1] * a1[1]);
;                         w.w = cvt_pk_bf16(__builtin_bit_cast(float, r.w << 16) + gv[bj][1][2] * a1[2], __builtin_bit_cast(float, r.w & 0xffff0000u) + gv[bj][1][3] * a1[3]);
;                         *(u32x4*)(out + off + bj * HALF) = w; } }
	v_lshl_add_u64 v[76:77], v[76:77], 0, v[186:187]
	v_fmac_f32_e32 v74, v75, v131
	flat_store_dwordx4 v[76:77], v[80:83]
	v_cvt_pk_bf16_f32 v72, v78, v72
	v_cvt_pk_bf16_f32 v73, v73, v74
	v_lshlrev_b32_e32 v74, 16, v150
	v_fmac_f32_e32 v74, v68, v124
	v_and_b32_e32 v68, 0xffff0000, v150
	v_fmac_f32_e32 v68, v69, v125
	v_cvt_pk_bf16_f32 v74, v74, v68
	v_lshlrev_b32_e32 v68, 16, v151
	v_and_b32_e32 v69, 0xffff0000, v151
	v_fmac_f32_e32 v68, v70, v126
	v_fmac_f32_e32 v69, v71, v127
	v_cvt_pk_bf16_f32 v75, v68, v69
	flat_store_dwordx4 v[76:77], v[72:75] offset:256
	v_lshl_add_u64 v[100:101], v[190:191], 0, s[20:21]
	v_lshl_add_u64 v[68:69], v[188:189], 0, v[100:101]
	flat_load_dwordx4 v[72:75], v[68:69]
	flat_load_dwordx4 v[76:79], v[68:69] offset:256
	s_mov_b64 s[20:21], 0x90000
	v_lshl_add_u64 v[102:103], v[190:191], 0, s[20:21]
	v_lshl_add_u64 v[68:69], v[188:189], 0, v[102:103]
	flat_load_dwordx4 v[80:83], v[68:69]
	flat_load_dwordx4 v[84:87], v[68:69] offset:256
	s_mov_b64 s[20:21], 0xa0000
	v_lshl_add_u64 v[104:105], v[190:191], 0, s[20:21]
	v_lshl_add_u64 v[68:69], v[188:189], 0, v[104:105]
	flat_load_dwordx4 v[88:91], v[68:69]
	flat_load_dwordx4 v[92:95], v[68:69] offset:256
	s_mov_b64 s[20:21], 0xb0000
	v_lshl_add_u64 v[106:107], v[190:191], 0, s[20:21]
	v_lshl_add_u64 v[68:69], v[188:189], 0, v[106:107]
	flat_load_dwordx4 v[96:99], v[68:69]
	s_nop 0
	flat_load_dwordx4 v[68:71], v[68:69] offset:256
	s_mov_b64 s[20:21], s[16:17]
	s_waitcnt vmcnt(0) lgkmcnt(0)
; __device__ __forceinline__ unsigned cvt_pk_bf16(float lo, float hi) { unsigned r; asm volatile("v_cvt_pk_bf16_f32 %0, %1, %2" : "=v"(r) : "v"(lo), "v"(hi)); return r; }
; #define PG8_WAIT_V(n) asm volatile("s_waitcnt vmcnt(" #n ")" ::: "memory")
; #define PG8_BAR __builtin_amdgcn_s_barrier()
;     __device__ __forceinline__ void operator()(const f32x4 (&acc)[2][2][4][2], const Unit& u, int wr, int wc, int fr, int fq) const {
;     ...
;                 for (int m = 0; m < 4; ++m) { const size_t off = (size_t)(row0 + ai * HALF + m * 16) * ldc + col0;
; #pragma unroll
;                     for (int bj = 0; bj < 2; ++bj) { const u32x4 r = bs[m][bj]; const f32x4 a0 = acc[ai][bj][m][0], a1 = acc[ai][bj][m][1];
;                         u32x4 w;
;                         w.x = cvt_pk_bf16(__builtin_bit_cast(float, r.x << 16) + gv[bj][0][0] * a0[0], __builtin_bit_cast(float, r.x & 0xffff0000u) + gv[bj][0][1] * a0[1]);
;                         w.y = cvt_pk_bf16(__builtin_bit_cast(float, r.y << 16) + gv[bj][0][2] * a0[2], __builtin_bit_cast(float, r.y & 0xffff0000u) + gv[bj][0][3] * a0[3]);
;                         w.z = cvt_pk_bf16(__builtin_bit_cast(float, r.z << 16) + gv[bj][1][0] * a1[0], __builtin_bit_cast(float, r.z & 0xffff0000u) + gv[bj][1][1] * a1[1]);
;                         w.w = cvt_pk_bf16(__builtin_bit_cast(float, r.w << 16) + gv[bj][1][2] * a1[2], __builtin_bit_cast(float, r.w & 0xffff0000u) + gv[bj][1][3] * a1[3]);
;                         *(u32x4*)(out + off + bj * HALF) = w; } }
; template <class Epi, class Sched, bool ALIGN_EPI = false, bool SP2 = false>
; __device__ __forceinline__ void gemm_phase(PG8_LAS unsigned char* lds, const Gemm g, const Sched& S, const Epi& E) {
;     ...
;     PG8_WAIT_V(0);
;     if constexpr (!ALIGN_EPI) { if (wr == 0) PG8_BAR; }
;     PG8_BAR;
	v_lshlrev_b32_e32 v108, 16, v72
	v_fmac_f32_e32 v108, v64, v136
	v_and_b32_e32 v64, 0xffff0000, v72
	v_fmac_f32_e32 v64, v65, v137
	v_lshlrev_b32_e32 v65, 16, v73
	v_fmac_f32_e32 v65, v66, v138
	v_and_b32_e32 v66, 0xffff0000, v73
	v_fmac_f32_e32 v66, v67, v139
	v_cvt_pk_bf16_f32 v64, v108, v64
	v_cvt_pk_bf16_f32 v65, v65, v66
	v_lshlrev_b32_e32 v66, 16, v74
	v_fmac_f32_e32 v66, v60, v132
	v_and_b32_e32 v60, 0xffff0000, v74
	v_fmac_f32_e32 v60, v61, v133
	v_cvt_pk_bf16_f32 v66, v66, v60
	v_lshlrev_b32_e32 v60, 16, v75
	v_fmac_f32_e32 v60, v62, v134
	v_lshlrev_b32_e32 v62, 16, v76
	v_and_b32_e32 v61, 0xffff0000, v75
	v_fmac_f32_e32 v62, v56, v128
	v_and_b32_e32 v56, 0xffff0000, v76
	v_fmac_f32_e32 v61, v63, v135
	v_fmac_f32_e32 v56, v57, v129
	v_lshlrev_b32_e32 v57, 16, v77
	v_cvt_pk_bf16_f32 v67, v60, v61
	v_lshl_add_u64 v[60:61], s[14:15], 0, v[100:101]
	v_fmac_f32_e32 v57, v58, v130
	v_and_b32_e32 v58, 0xffff0000, v77
	v_lshl_add_u64 v[60:61], v[60:61], 0, v[186:187]
	v_fmac_f32_e32 v58, v59, v131
	flat_store_dwordx4 v[60:61], v[64:67]
	v_cvt_pk_bf16_f32 v56, v62, v56
	v_cvt_pk_bf16_f32 v57, v57, v58
	v_lshlrev_b32_e32 v58, 16, v78
	v_fmac_f32_e32 v58, v48, v124
	v_and_b32_e32 v48, 0xffff0000, v78
	v_fmac_f32_e32 v48, v49, v125
	v_cvt_pk_bf16_f32 v58, v58, v48
	v_lshlrev_b32_e32 v48, 16, v79
	v_and_b32_e32 v49, 0xffff0000, v79
	v_fmac_f32_e32 v48, v50, v126
	v_fmac_f32_e32 v49, v51, v127
	v_cvt_pk_bf16_f32 v59, v48, v49
	v_lshlrev_b32_e32 v48, 16, v80
	v_and_b32_e32 v49, 0xffff0000, v80
	v_fmac_f32_e32 v48, v52, v136
	v_fmac_f32_e32 v49, v53, v137
	flat_store_dwordx4 v[60:61], v[56:59] offset:256
	v_cvt_pk_bf16_f32 v48, v48, v49
	v_lshlrev_b32_e32 v49, 16, v81
	v_and_b32_e32 v50, 0xffff0000, v81
	v_fmac_f32_e32 v49, v54, v138
	v_fmac_f32_e32 v50, v55, v139
	v_cvt_pk_bf16_f32 v49, v49, v50
	v_lshlrev_b32_e32 v50, 16, v82
	v_fmac_f32_e32 v50, v44, v132
	v_and_b32_e32 v44, 0xffff0000, v82
	v_fmac_f32_e32 v44, v45, v133
	v_cvt_pk_bf16_f32 v50, v50, v44
	v_lshlrev_b32_e32 v44, 16, v83
	v_fmac_f32_e32 v44, v46, v134
	v_lshlrev_b32_e32 v46, 16, v84
	v_and_b32_e32 v45, 0xffff0000, v83
	v_fmac_f32_e32 v46, v40, v128
	v_and_b32_e32 v40, 0xffff0000, v84
	v_fmac_f32_e32 v45, v47, v135
	v_fmac_f32_e32 v40, v41, v129
	v_lshlrev_b32_e32 v41, 16, v85
	v_cvt_pk_bf16_f32 v51, v44, v45
	v_lshl_add_u64 v[44:45], s[14:15], 0, v[102:103]
	v_fmac_f32_e32 v41, v42, v130
	v_and_b32_e32 v42, 0xffff0000, v85
	v_lshl_add_u64 v[44:45], v[44:45], 0, v[186:187]
	v_fmac_f32_e32 v42, v43, v131
	flat_store_dwordx4 v[44:45], v[48:51]
	v_cvt_pk_bf16_f32 v40, v46, v40
	v_cvt_pk_bf16_f32 v41, v41, v42
	v_lshlrev_b32_e32 v42, 16, v86
	v_fmac_f32_e32 v42, v32, v124
	v_and_b32_e32 v32, 0xffff0000, v86
	v_fmac_f32_e32 v32, v33, v125
	v_cvt_pk_bf16_f32 v42, v42, v32
	v_lshlrev_b32_e32 v32, 16, v87
	v_and_b32_e32 v33, 0xffff0000, v87
	v_fmac_f32_e32 v32, v34, v126
	v_fmac_f32_e32 v33, v35, v127
	v_cvt_pk_bf16_f32 v43, v32, v33
	v_lshlrev_b32_e32 v32, 16, v88
	v_and_b32_e32 v33, 0xffff0000, v88
	v_fmac_f32_e32 v32, v36, v136
	v_fmac_f32_e32 v33, v37, v137
	flat_store_dwordx4 v[44:45], v[40:43] offset:256
	v_cvt_pk_bf16_f32 v32, v32, v33
	v_lshlrev_b32_e32 v33, 16, v89
	v_and_b32_e32 v34, 0xffff0000, v89
	v_fmac_f32_e32 v33, v38, v138
	v_fmac_f32_e32 v34, v39, v139
	v_cvt_pk_bf16_f32 v33, v33, v34
	v_lshlrev_b32_e32 v34, 16, v90
	v_fmac_f32_e32 v34, v28, v132
	v_and_b32_e32 v28, 0xffff0000, v90
	v_fmac_f32_e32 v28, v29, v133
	v_cvt_pk_bf16_f32 v34, v34, v28
	v_lshlrev_b32_e32 v28, 16, v91
	v_fmac_f32_e32 v28, v30, v134
	v_lshlrev_b32_e32 v30, 16, v92
	v_and_b32_e32 v29, 0xffff0000, v91
	v_fmac_f32_e32 v30, v24, v128
	v_and_b32_e32 v24, 0xffff0000, v92
	v_fmac_f32_e32 v29, v31, v135
	v_fmac_f32_e32 v24, v25, v129
	v_lshlrev_b32_e32 v25, 16, v93
	v_cvt_pk_bf16_f32 v35, v28, v29
	v_lshl_add_u64 v[28:29], s[14:15], 0, v[104:105]
	v_fmac_f32_e32 v25, v26, v130
	v_and_b32_e32 v26, 0xffff0000, v93
	v_lshl_add_u64 v[28:29], v[28:29], 0, v[186:187]
	v_fmac_f32_e32 v26, v27, v131
	flat_store_dwordx4 v[28:29], v[32:35]
	v_cvt_pk_bf16_f32 v24, v30, v24
	v_cvt_pk_bf16_f32 v25, v25, v26
	v_lshlrev_b32_e32 v26, 16, v94
	v_fmac_f32_e32 v26, v16, v124
	v_and_b32_e32 v16, 0xffff0000, v94
	v_fmac_f32_e32 v16, v17, v125
	v_cvt_pk_bf16_f32 v26, v26, v16
	v_lshlrev_b32_e32 v16, 16, v95
	v_and_b32_e32 v17, 0xffff0000, v95
	v_fmac_f32_e32 v16, v18, v126
	v_fmac_f32_e32 v17, v19, v127
	v_cvt_pk_bf16_f32 v27, v16, v17
	v_lshlrev_b32_e32 v16, 16, v96
	v_and_b32_e32 v17, 0xffff0000, v96
	v_fmac_f32_e32 v16, v20, v136
	v_fmac_f32_e32 v17, v21, v137
	flat_store_dwordx4 v[28:29], v[24:27] offset:256
	v_cvt_pk_bf16_f32 v16, v16, v17
	v_lshlrev_b32_e32 v17, 16, v97
	v_and_b32_e32 v18, 0xffff0000, v97
	v_fmac_f32_e32 v17, v22, v138
	v_fmac_f32_e32 v18, v23, v139
	v_cvt_pk_bf16_f32 v17, v17, v18
	v_lshlrev_b32_e32 v18, 16, v98
	v_fmac_f32_e32 v18, v12, v132
	v_and_b32_e32 v12, 0xffff0000, v98
	v_fmac_f32_e32 v12, v13, v133
	v_cvt_pk_bf16_f32 v18, v18, v12
	v_lshlrev_b32_e32 v12, 16, v99
	v_fmac_f32_e32 v12, v14, v134
	v_lshlrev_b32_e32 v14, 16, v68
	v_and_b32_e32 v13, 0xffff0000, v99
	v_fmac_f32_e32 v14, v8, v128
	v_and_b32_e32 v8, 0xffff0000, v68
	v_fmac_f32_e32 v13, v15, v135
	v_fmac_f32_e32 v8, v9, v129
	v_lshlrev_b32_e32 v9, 16, v69
	v_cvt_pk_bf16_f32 v19, v12, v13
	v_lshl_add_u64 v[12:13], s[14:15], 0, v[106:107]
	v_fmac_f32_e32 v9, v10, v130
	v_and_b32_e32 v10, 0xffff0000, v69
	v_lshl_add_u64 v[12:13], v[12:13], 0, v[186:187]
	v_fmac_f32_e32 v10, v11, v131
	flat_store_dwordx4 v[12:13], v[16:19]
	v_cvt_pk_bf16_f32 v8, v14, v8
	v_cvt_pk_bf16_f32 v9, v9, v10
	v_lshlrev_b32_e32 v10, 16, v70
	v_fmac_f32_e32 v10, v4, v124
	v_and_b32_e32 v4, 0xffff0000, v70
	v_fmac_f32_e32 v4, v5, v125
	v_cvt_pk_bf16_f32 v10, v10, v4
	v_lshlrev_b32_e32 v4, 16, v71
	v_and_b32_e32 v5, 0xffff0000, v71
	v_fmac_f32_e32 v4, v6, v126
	v_fmac_f32_e32 v5, v7, v127
	v_cvt_pk_bf16_f32 v11, v4, v5
	flat_store_dwordx4 v[12:13], v[8:11] offset:256
	s_cbranch_vccz .LBB0_2227
	s_waitcnt vmcnt(0)
	s_cmpk_gt_u32 s7, 0xff
	s_cbranch_scc1 .LBB0_2242
	s_barrier
